# redundant waits (asm guide 5): 20 already-satisfied lgkmcnt(0) at GEMM compute-block starts deleted (an lgkmcnt(0) with no LDS op in between precedes each), on top of v39
# baseline (speedup 1.0000x reference)
; #define PG8_STAGE(bufoff, gbase, voff) do { _Pragma("unroll") for (int _i = 0; _i < 2; ++_i) \
;         __builtin_amdgcn_global_load_lds((const unsigned*)((const char*)(gbase) + (voff)[_i]), (PG8_LAS unsigned*)(lds + (bufoff) + ldsw + _i * 8192), 16, 0, 0); } while (0)
; #define PG8_LDA(dst, b, h) do { _Pragma("unroll") for (int m = 0; m < 4; ++m) _Pragma("unroll") for (int k = 0; k < 2; ++k) dst[m][k] = *(const PG8_LAS bf16x8*)(lds + PG8_SA(b, h) + aoff + m * 2048 + k * 1024); } while (0)
; #define PG8_LDB(dst, b, h) do { _Pragma("unroll") for (int n = 0; n < 2; ++n) _Pragma("unroll") for (int k = 0; k < 2; ++k) dst[n][k] = *(const PG8_LAS bf16x8*)(lds + PG8_SB(b, h) + boff + n * 2048 + k * 1024); } while (0)
; #define PG8_MMA(ai, bj, At, Bt) do { __builtin_amdgcn_s_setprio(1); _Pragma("unroll") for (int m = 0; m < 4; ++m) _Pragma("unroll") for (int n = 0; n < 2; ++n) _Pragma("unroll") for (int k = 0; k < 2; ++k) \
;         acc[ai][bj][m][n] = __builtin_amdgcn_mfma_f32_16x16x32_bf16(Bt[n][k], At[m][k], acc[ai][bj][m][n], 0, 0, 0); __builtin_amdgcn_s_setprio(0); } while (0)
; #define PG8_WAIT_V(n) asm volatile("s_waitcnt vmcnt(" #n ")" ::: "memory")
; #define PG8_BAR __builtin_amdgcn_s_barrier()
; template <class Epi, class Sched, bool ALIGN_EPI = false, bool SP2 = false>
; __device__ __forceinline__ void gemm_phase(PG8_LAS unsigned char* lds, const Gemm g, const Sched& S, const Epi& E) {
;     ...
;         for (int t = 0; t < ntu; t += 2) {
;             const bool last = (t == ntu - 2);
;             const char* a1 = cA + (size_t)(t + 1) * kstep;
;             const char* a2 = last ? nA : cA + (size_t)(t + 2) * kstep; const char* b2 = last ? nB : cB + (size_t)(t + 2) * kstep;
;             const char* a3 = a2 + kstep; const char* b3 = b2 + kstep;
;             if (last && has_next) S.a_ready(nxt);
;             if constexpr (SP2) {
;             PG8_LDB(B0, 0, 0); PG8_LDB(B1, 0, 1); PG8_SCHED; PG8_LDA(At, 0, 0); PG8_STAGE(PG8_SA(1, 1), a1 + hstep, voffA);
;             PG8_WAIT_V(8); PG8_WAIT_L(0); PG8_BAR; PG8_MMA(0, 0, At, B0); PG8_MMA(0, 1, At, B1); PG8_BAR; PG8_SCHED;
;             PG8_LDA(At, 0, 1); PG8_STAGE(PG8_SB(0, 0), b2, voffB); PG8_STAGE(PG8_SB(0, 1), b2 + hstep, voffB); PG8_STAGE(PG8_SA(0, 0), a2, voffA);
;             PG8_WAIT_V(8); PG8_WAIT_L(0); PG8_BAR; if (full) { PG8_MMA(1, 0, At, B0); PG8_MMA(1, 1, At, B1); } PG8_BAR; PG8_SCHED;
.LBB0_166:
	s_add_u32 s2, s48, 0xfffc0080
	s_addc_u32 s3, s49, -1
	s_add_i32 s4, 0, 0x10000
	s_cmp_eq_u32 s12, 12
	s_cselect_b32 s35, s81, s3
	s_cselect_b32 s34, s94, s2
	v_add_u32_e32 v128, s4, v228
	s_cselect_b32 s29, s79, s51
	s_cselect_b32 s28, s95, s50
	s_add_i32 s5, 0, 0x14000
	ds_read_b128 v[146:149], v128
	ds_read_b128 v[150:153], v128 offset:1024
	ds_read_b128 v[154:157], v128 offset:2048
	ds_read_b128 v[158:161], v128 offset:3072
	v_add_u32_e32 v128, s5, v228
	ds_read_b128 v[130:133], v128
	ds_read_b128 v[134:137], v128 offset:1024
	ds_read_b128 v[138:141], v128 offset:2048
	ds_read_b128 v[142:145], v128 offset:3072
	v_lshl_add_u64 v[196:197], s[48:49], 0, v[216:217]
	s_add_i32 m0, s70, 0xc000
	s_waitcnt lgkmcnt(7)
	ds_read_b128 v[162:165], v248
	ds_read_b128 v[166:169], v248 offset:1024
	ds_read_b128 v[170:173], v248 offset:2048
	ds_read_b128 v[174:177], v248 offset:3072
	ds_read_b128 v[178:181], v248 offset:4096
	ds_read_b128 v[182:185], v248 offset:5120
	ds_read_b128 v[186:189], v248 offset:6144
	ds_read_b128 v[190:193], v248 offset:7168
	global_load_lds_dwordx4 v[196:197], off
	v_lshl_add_u64 v[196:197], s[48:49], 0, v[218:219]
	s_add_i32 m0, s70, 0xe000
	s_nop 0
	global_load_lds_dwordx4 v[196:197], off
	s_waitcnt vmcnt(8)
	s_waitcnt lgkmcnt(0)
	s_barrier
	s_setprio 1
	v_mfma_f32_16x16x32_bf16 v[124:127], v[146:149], v[162:165], v[124:127]
	v_mfma_f32_16x16x32_bf16 v[120:123], v[154:157], v[162:165], v[120:123]
	v_mfma_f32_16x16x32_bf16 v[108:111], v[146:149], v[170:173], v[108:111]
	v_mfma_f32_16x16x32_bf16 v[104:107], v[154:157], v[170:173], v[104:107]
	v_mfma_f32_16x16x32_bf16 v[92:95], v[146:149], v[178:181], v[92:95]
	v_mfma_f32_16x16x32_bf16 v[88:91], v[154:157], v[178:181], v[88:91]
	v_mfma_f32_16x16x32_bf16 v[76:79], v[146:149], v[186:189], v[76:79]
	v_mfma_f32_16x16x32_bf16 v[72:75], v[154:157], v[186:189], v[72:75]
	v_mfma_f32_16x16x32_bf16 v[124:127], v[150:153], v[166:169], v[124:127]
	v_mfma_f32_16x16x32_bf16 v[120:123], v[158:161], v[166:169], v[120:123]
	v_mfma_f32_16x16x32_bf16 v[108:111], v[150:153], v[174:177], v[108:111]
	v_mfma_f32_16x16x32_bf16 v[104:107], v[158:161], v[174:177], v[104:107]
	v_mfma_f32_16x16x32_bf16 v[92:95], v[150:153], v[182:185], v[92:95]
	v_mfma_f32_16x16x32_bf16 v[88:91], v[158:161], v[182:185], v[88:91]
	v_mfma_f32_16x16x32_bf16 v[76:79], v[150:153], v[190:193], v[76:79]
	v_mfma_f32_16x16x32_bf16 v[72:75], v[158:161], v[190:193], v[72:75]
	v_mfma_f32_16x16x32_bf16 v[116:119], v[130:133], v[162:165], v[116:119]
	v_mfma_f32_16x16x32_bf16 v[112:115], v[138:141], v[162:165], v[112:115]
	v_mfma_f32_16x16x32_bf16 v[100:103], v[130:133], v[170:173], v[100:103]
	v_mfma_f32_16x16x32_bf16 v[96:99], v[138:141], v[170:173], v[96:99]
	v_mfma_f32_16x16x32_bf16 v[84:87], v[130:133], v[178:181], v[84:87]
	v_mfma_f32_16x16x32_bf16 v[80:83], v[138:141], v[178:181], v[80:83]
	v_mfma_f32_16x16x32_bf16 v[68:71], v[130:133], v[186:189], v[68:71]
	v_mfma_f32_16x16x32_bf16 v[64:67], v[138:141], v[186:189], v[64:67]
	v_mfma_f32_16x16x32_bf16 v[116:119], v[134:137], v[166:169], v[116:119]
	v_mfma_f32_16x16x32_bf16 v[112:115], v[142:145], v[166:169], v[112:115]
	v_mfma_f32_16x16x32_bf16 v[100:103], v[134:137], v[174:177], v[100:103]
	v_mfma_f32_16x16x32_bf16 v[96:99], v[142:145], v[174:177], v[96:99]
	v_mfma_f32_16x16x32_bf16 v[84:87], v[134:137], v[182:185], v[84:87]
	v_mfma_f32_16x16x32_bf16 v[80:83], v[142:145], v[182:185], v[80:83]
	v_mfma_f32_16x16x32_bf16 v[68:71], v[134:137], v[190:193], v[68:71]
	v_mfma_f32_16x16x32_bf16 v[64:67], v[142:145], v[190:193], v[64:67]
	s_setprio 0
	s_barrier
	s_add_i32 s2, s4, s65
	v_lshl_add_u64 v[220:221], s[28:29], 0, v[208:209]
	s_mov_b32 m0, s2
	ds_read_b128 v[186:189], v248 offset:16384
	ds_read_b128 v[190:193], v248 offset:17408
	ds_read_b128 v[178:181], v248 offset:18432
	ds_read_b128 v[182:185], v248 offset:19456
	ds_read_b128 v[170:173], v248 offset:20480
	ds_read_b128 v[174:177], v248 offset:21504
	ds_read_b128 v[162:165], v248 offset:22528
	ds_read_b128 v[166:169], v248 offset:23552
	global_load_lds_dwordx4 v[220:221], off
	s_add_i32 m0, s2, 0x2000
	s_add_u32 s2, s28, 0x40000
	v_lshl_add_u64 v[222:223], s[28:29], 0, v[212:213]
	s_addc_u32 s3, s29, 0
	s_add_i32 s4, s5, s65
	global_load_lds_dwordx4 v[222:223], off
	v_lshl_add_u64 v[196:197], s[2:3], 0, v[208:209]
	s_mov_b32 m0, s4
	v_lshl_add_u64 v[224:225], s[34:35], 0, v[206:207]
	global_load_lds_dwordx4 v[196:197], off
	v_lshl_add_u64 v[196:197], s[2:3], 0, v[212:213]
	s_add_i32 m0, s4, 0x2000
	v_lshl_add_u64 v[226:227], s[34:35], 0, v[210:211]
	global_load_lds_dwordx4 v[196:197], off
	s_mov_b32 m0, s70
	v_cndmask_b32_e64 v128, 0, 1, s[30:31]
	global_load_lds_dwordx4 v[224:225], off
	s_mov_b32 m0, s71
	v_cmp_ne_u32_e64 s[42:43], 1, v128
	global_load_lds_dwordx4 v[226:227], off
	s_waitcnt vmcnt(8)
	s_waitcnt lgkmcnt(0)
	s_andn2_b64 vcc, exec, s[30:31]
	s_barrier
	s_cbranch_vccnz .LBB0_168
; #define PG8_MMA(ai, bj, At, Bt) do { __builtin_amdgcn_s_setprio(1); _Pragma("unroll") for (int m = 0; m < 4; ++m) _Pragma("unroll") for (int n = 0; n < 2; ++n) _Pragma("unroll") for (int k = 0; k < 2; ++k) \
;         acc[ai][bj][m][n] = __builtin_amdgcn_mfma_f32_16x16x32_bf16(Bt[n][k], At[m][k], acc[ai][bj][m][n], 0, 0, 0); __builtin_amdgcn_s_setprio(0); } while (0)
; #define PG8_WAIT_V(n) asm volatile("s_waitcnt vmcnt(" #n ")" ::: "memory")
; #define PG8_WAIT_L(n) asm volatile("s_waitcnt lgkmcnt(" #n ")" ::: "memory")
; #define PG8_BAR __builtin_amdgcn_s_barrier()
; #define PG8_SCHED __builtin_amdgcn_sched_barrier(0)
; template <class Epi, class Sched, bool ALIGN_EPI = false, bool SP2 = false>
; __device__ __forceinline__ void gemm_phase(PG8_LAS unsigned char* lds, const Gemm g, const Sched& S, const Epi& E) {
;     ...
;             PG8_WAIT_V(8); PG8_WAIT_L(0); PG8_BAR; if (full) { PG8_MMA(1, 0, At, B0); PG8_MMA(1, 1, At, B1); } PG8_BAR; PG8_SCHED;
	s_setprio 1
	v_mfma_f32_16x16x32_bf16 v[60:63], v[146:149], v[186:189], v[60:63]
	v_mfma_f32_16x16x32_bf16 v[56:59], v[154:157], v[186:189], v[56:59]
	v_mfma_f32_16x16x32_bf16 v[44:47], v[146:149], v[178:181], v[44:47]
	v_mfma_f32_16x16x32_bf16 v[40:43], v[154:157], v[178:181], v[40:43]
	v_mfma_f32_16x16x32_bf16 v[28:31], v[146:149], v[170:173], v[28:31]
	v_mfma_f32_16x16x32_bf16 v[24:27], v[154:157], v[170:173], v[24:27]
	v_mfma_f32_16x16x32_bf16 v[12:15], v[146:149], v[162:165], v[12:15]
	v_mfma_f32_16x16x32_bf16 v[8:11], v[154:157], v[162:165], v[8:11]
	v_mfma_f32_16x16x32_bf16 v[60:63], v[150:153], v[190:193], v[60:63]
	v_mfma_f32_16x16x32_bf16 v[56:59], v[158:161], v[190:193], v[56:59]
	v_mfma_f32_16x16x32_bf16 v[44:47], v[150:153], v[182:185], v[44:47]
	v_mfma_f32_16x16x32_bf16 v[40:43], v[158:161], v[182:185], v[40:43]
	v_mfma_f32_16x16x32_bf16 v[28:31], v[150:153], v[174:177], v[28:31]
	v_mfma_f32_16x16x32_bf16 v[24:27], v[158:161], v[174:177], v[24:27]
	v_mfma_f32_16x16x32_bf16 v[12:15], v[150:153], v[166:169], v[12:15]
	v_mfma_f32_16x16x32_bf16 v[8:11], v[158:161], v[166:169], v[8:11]
	v_mfma_f32_16x16x32_bf16 v[52:55], v[130:133], v[186:189], v[52:55]
	v_mfma_f32_16x16x32_bf16 v[48:51], v[138:141], v[186:189], v[48:51]
	v_mfma_f32_16x16x32_bf16 v[36:39], v[130:133], v[178:181], v[36:39]
	v_mfma_f32_16x16x32_bf16 v[32:35], v[138:141], v[178:181], v[32:35]
	v_mfma_f32_16x16x32_bf16 v[20:23], v[130:133], v[170:173], v[20:23]
	v_mfma_f32_16x16x32_bf16 v[16:19], v[138:141], v[170:173], v[16:19]
	v_mfma_f32_16x16x32_bf16 v[4:7], v[130:133], v[162:165], v[4:7]
	v_mfma_f32_16x16x32_bf16 v[0:3], v[138:141], v[162:165], v[0:3]
	v_mfma_f32_16x16x32_bf16 v[52:55], v[134:137], v[190:193], v[52:55]
	v_mfma_f32_16x16x32_bf16 v[48:51], v[142:145], v[190:193], v[48:51]
	v_mfma_f32_16x16x32_bf16 v[36:39], v[134:137], v[182:185], v[36:39]
	v_mfma_f32_16x16x32_bf16 v[32:35], v[142:145], v[182:185], v[32:35]
	v_mfma_f32_16x16x32_bf16 v[20:23], v[134:137], v[174:177], v[20:23]
	v_mfma_f32_16x16x32_bf16 v[16:19], v[142:145], v[174:177], v[16:19]
	v_mfma_f32_16x16x32_bf16 v[4:7], v[134:137], v[166:169], v[4:7]
	v_mfma_f32_16x16x32_bf16 v[0:3], v[142:145], v[166:169], v[0:3]
	s_setprio 0
; #define PG8_STAGE(bufoff, gbase, voff) do { _Pragma("unroll") for (int _i = 0; _i < 2; ++_i) \
;         __builtin_amdgcn_global_load_lds((const unsigned*)((const char*)(gbase) + (voff)[_i]), (PG8_LAS unsigned*)(lds + (bufoff) + ldsw + _i * 8192), 16, 0, 0); } while (0)
; #define PG8_LDA(dst, b, h) do { _Pragma("unroll") for (int m = 0; m < 4; ++m) _Pragma("unroll") for (int k = 0; k < 2; ++k) dst[m][k] = *(const PG8_LAS bf16x8*)(lds + PG8_SA(b, h) + aoff + m * 2048 + k * 1024); } while (0)
; #define PG8_LDB(dst, b, h) do { _Pragma("unroll") for (int n = 0; n < 2; ++n) _Pragma("unroll") for (int k = 0; k < 2; ++k) dst[n][k] = *(const PG8_LAS bf16x8*)(lds + PG8_SB(b, h) + boff + n * 2048 + k * 1024); } while (0)
; #define PG8_MMA(ai, bj, At, Bt) do { __builtin_amdgcn_s_setprio(1); _Pragma("unroll") for (int m = 0; m < 4; ++m) _Pragma("unroll") for (int n = 0; n < 2; ++n) _Pragma("unroll") for (int k = 0; k < 2; ++k) \
;         acc[ai][bj][m][n] = __builtin_amdgcn_mfma_f32_16x16x32_bf16(Bt[n][k], At[m][k], acc[ai][bj][m][n], 0, 0, 0); __builtin_amdgcn_s_setprio(0); } while (0)
; #define PG8_WAIT_V(n) asm volatile("s_waitcnt vmcnt(" #n ")" ::: "memory")
; #define PG8_WAIT_L(n) asm volatile("s_waitcnt lgkmcnt(" #n ")" ::: "memory")
; #define PG8_BAR __builtin_amdgcn_s_barrier()
; #define PG8_SCHED __builtin_amdgcn_sched_barrier(0)
; template <class Epi, class Sched, bool ALIGN_EPI = false, bool SP2 = false>
; __device__ __forceinline__ void gemm_phase(PG8_LAS unsigned char* lds, const Gemm g, const Sched& S, const Epi& E) {
;     ...
;             PG8_LDB(B0, 1, 0); PG8_LDB(B1, 1, 1); PG8_SCHED; PG8_LDA(At, 1, 0); PG8_STAGE(PG8_SA(0, 1), a2 + hstep, voffA);
;             PG8_WAIT_V(8); PG8_WAIT_L(0); PG8_BAR; PG8_MMA(0, 0, At, B0); PG8_MMA(0, 1, At, B1); PG8_BAR; PG8_SCHED;
;             PG8_LDA(At, 1, 1); PG8_STAGE(PG8_SB(1, 0), b3, voffB); PG8_STAGE(PG8_SB(1, 1), b3 + hstep, voffB); PG8_STAGE(PG8_SA(1, 0), a3, voffA);
;             PG8_WAIT_V(8); PG8_WAIT_L(0); PG8_BAR; if (full) { PG8_MMA(1, 0, At, B0); PG8_MMA(1, 1, At, B1); } PG8_BAR; PG8_SCHED;
.LBB0_168:
	s_barrier
	s_add_i32 s4, 0, 0x18000
	v_add_u32_e32 v128, s4, v228
	s_add_i32 s5, 0, 0x1c000
	ds_read_b128 v[146:149], v128
	ds_read_b128 v[150:153], v128 offset:1024
	ds_read_b128 v[154:157], v128 offset:2048
	ds_read_b128 v[158:161], v128 offset:3072
	v_add_u32_e32 v128, s5, v228
	ds_read_b128 v[130:133], v128
	ds_read_b128 v[134:137], v128 offset:1024
	ds_read_b128 v[138:141], v128 offset:2048
	ds_read_b128 v[142:145], v128 offset:3072
	s_add_u32 s2, s34, 0x40000
	s_addc_u32 s3, s35, 0
	s_mov_b32 m0, s73
	v_lshl_add_u64 v[196:197], s[2:3], 0, v[206:207]
	s_waitcnt lgkmcnt(7)
	ds_read_b128 v[162:165], v248 offset:32768
	ds_read_b128 v[166:169], v248 offset:33792
	ds_read_b128 v[170:173], v248 offset:34816
	ds_read_b128 v[174:177], v248 offset:35840
	ds_read_b128 v[178:181], v248 offset:36864
	ds_read_b128 v[182:185], v248 offset:37888
	ds_read_b128 v[186:189], v248 offset:38912
	ds_read_b128 v[190:193], v248 offset:39936
	global_load_lds_dwordx4 v[196:197], off
	v_lshl_add_u64 v[196:197], s[2:3], 0, v[210:211]
	s_mov_b32 m0, s87
	s_nop 0
	global_load_lds_dwordx4 v[196:197], off
	s_waitcnt vmcnt(8)
	s_waitcnt lgkmcnt(0)
	s_barrier
	s_setprio 1
	v_mfma_f32_16x16x32_bf16 v[124:127], v[146:149], v[162:165], v[124:127]
	v_mfma_f32_16x16x32_bf16 v[120:123], v[154:157], v[162:165], v[120:123]
	v_mfma_f32_16x16x32_bf16 v[108:111], v[146:149], v[170:173], v[108:111]
	v_mfma_f32_16x16x32_bf16 v[104:107], v[154:157], v[170:173], v[104:107]
	v_mfma_f32_16x16x32_bf16 v[92:95], v[146:149], v[178:181], v[92:95]
	v_mfma_f32_16x16x32_bf16 v[88:91], v[154:157], v[178:181], v[88:91]
	v_mfma_f32_16x16x32_bf16 v[76:79], v[146:149], v[186:189], v[76:79]
	v_mfma_f32_16x16x32_bf16 v[72:75], v[154:157], v[186:189], v[72:75]
	v_mfma_f32_16x16x32_bf16 v[124:127], v[150:153], v[166:169], v[124:127]
	v_mfma_f32_16x16x32_bf16 v[120:123], v[158:161], v[166:169], v[120:123]
	v_mfma_f32_16x16x32_bf16 v[108:111], v[150:153], v[174:177], v[108:111]
	v_mfma_f32_16x16x32_bf16 v[104:107], v[158:161], v[174:177], v[104:107]
	v_mfma_f32_16x16x32_bf16 v[92:95], v[150:153], v[182:185], v[92:95]
	v_mfma_f32_16x16x32_bf16 v[88:91], v[158:161], v[182:185], v[88:91]
	v_mfma_f32_16x16x32_bf16 v[76:79], v[150:153], v[190:193], v[76:79]
	v_mfma_f32_16x16x32_bf16 v[72:75], v[158:161], v[190:193], v[72:75]
	v_mfma_f32_16x16x32_bf16 v[116:119], v[130:133], v[162:165], v[116:119]
	v_mfma_f32_16x16x32_bf16 v[112:115], v[138:141], v[162:165], v[112:115]
	v_mfma_f32_16x16x32_bf16 v[100:103], v[130:133], v[170:173], v[100:103]
	v_mfma_f32_16x16x32_bf16 v[96:99], v[138:141], v[170:173], v[96:99]
	v_mfma_f32_16x16x32_bf16 v[84:87], v[130:133], v[178:181], v[84:87]
	v_mfma_f32_16x16x32_bf16 v[80:83], v[138:141], v[178:181], v[80:83]
	v_mfma_f32_16x16x32_bf16 v[68:71], v[130:133], v[186:189], v[68:71]
	v_mfma_f32_16x16x32_bf16 v[64:67], v[138:141], v[186:189], v[64:67]
	v_mfma_f32_16x16x32_bf16 v[116:119], v[134:137], v[166:169], v[116:119]
	v_mfma_f32_16x16x32_bf16 v[112:115], v[142:145], v[166:169], v[112:115]
	v_mfma_f32_16x16x32_bf16 v[100:103], v[134:137], v[174:177], v[100:103]
	v_mfma_f32_16x16x32_bf16 v[96:99], v[142:145], v[174:177], v[96:99]
	v_mfma_f32_16x16x32_bf16 v[84:87], v[134:137], v[182:185], v[84:87]
	v_mfma_f32_16x16x32_bf16 v[80:83], v[142:145], v[182:185], v[80:83]
	v_mfma_f32_16x16x32_bf16 v[68:71], v[134:137], v[190:193], v[68:71]
	v_mfma_f32_16x16x32_bf16 v[64:67], v[142:145], v[190:193], v[64:67]
	s_setprio 0
	s_barrier
	s_add_i32 s2, s4, s65
	v_lshl_add_u64 v[196:197], v[220:221], 0, s[26:27]
	s_mov_b32 m0, s2
	ds_read_b128 v[186:189], v248 offset:49152
	ds_read_b128 v[190:193], v248 offset:50176
	ds_read_b128 v[178:181], v248 offset:51200
	ds_read_b128 v[182:185], v248 offset:52224
	ds_read_b128 v[170:173], v248 offset:53248
	ds_read_b128 v[174:177], v248 offset:54272
	ds_read_b128 v[162:165], v248 offset:55296
	ds_read_b128 v[166:169], v248 offset:56320
	global_load_lds_dwordx4 v[196:197], off
	s_add_i32 m0, s2, 0x2000
	s_add_u32 s2, s28, 0x40080
	v_lshl_add_u64 v[196:197], v[222:223], 0, s[26:27]
	s_addc_u32 s3, s29, 0
	s_add_i32 s4, s5, s65
	global_load_lds_dwordx4 v[196:197], off
	v_lshl_add_u64 v[196:197], s[2:3], 0, v[208:209]
	s_mov_b32 m0, s4
	s_and_b64 vcc, exec, s[42:43]
	global_load_lds_dwordx4 v[196:197], off
	v_lshl_add_u64 v[196:197], s[2:3], 0, v[212:213]
	s_add_i32 m0, s4, 0x2000
	s_nop 0
	global_load_lds_dwordx4 v[196:197], off
	v_lshl_add_u64 v[196:197], v[224:225], 0, s[26:27]
	s_mov_b32 m0, s88
	s_nop 0
	global_load_lds_dwordx4 v[196:197], off
	v_lshl_add_u64 v[196:197], v[226:227], 0, s[26:27]
	s_mov_b32 m0, s89
	s_nop 0
	global_load_lds_dwordx4 v[196:197], off
	s_waitcnt vmcnt(8)
	s_waitcnt lgkmcnt(0)
	s_barrier
	s_cbranch_vccnz .LBB0_165
	s_setprio 1
	v_mfma_f32_16x16x32_bf16 v[60:63], v[146:149], v[186:189], v[60:63]
	v_mfma_f32_16x16x32_bf16 v[56:59], v[154:157], v[186:189], v[56:59]
	v_mfma_f32_16x16x32_bf16 v[44:47], v[146:149], v[178:181], v[44:47]
	v_mfma_f32_16x16x32_bf16 v[40:43], v[154:157], v[178:181], v[40:43]
	v_mfma_f32_16x16x32_bf16 v[28:31], v[146:149], v[170:173], v[28:31]
	v_mfma_f32_16x16x32_bf16 v[24:27], v[154:157], v[170:173], v[24:27]
	v_mfma_f32_16x16x32_bf16 v[12:15], v[146:149], v[162:165], v[12:15]
	v_mfma_f32_16x16x32_bf16 v[8:11], v[154:157], v[162:165], v[8:11]
	v_mfma_f32_16x16x32_bf16 v[60:63], v[150:153], v[190:193], v[60:63]
	v_mfma_f32_16x16x32_bf16 v[56:59], v[158:161], v[190:193], v[56:59]
	v_mfma_f32_16x16x32_bf16 v[44:47], v[150:153], v[182:185], v[44:47]
	v_mfma_f32_16x16x32_bf16 v[40:43], v[158:161], v[182:185], v[40:43]
	v_mfma_f32_16x16x32_bf16 v[28:31], v[150:153], v[174:177], v[28:31]
	v_mfma_f32_16x16x32_bf16 v[24:27], v[158:161], v[174:177], v[24:27]
	v_mfma_f32_16x16x32_bf16 v[12:15], v[150:153], v[166:169], v[12:15]
	v_mfma_f32_16x16x32_bf16 v[8:11], v[158:161], v[166:169], v[8:11]
	v_mfma_f32_16x16x32_bf16 v[52:55], v[130:133], v[186:189], v[52:55]
	v_mfma_f32_16x16x32_bf16 v[48:51], v[138:141], v[186:189], v[48:51]
	v_mfma_f32_16x16x32_bf16 v[36:39], v[130:133], v[178:181], v[36:39]
	v_mfma_f32_16x16x32_bf16 v[32:35], v[138:141], v[178:181], v[32:35]
	v_mfma_f32_16x16x32_bf16 v[20:23], v[130:133], v[170:173], v[20:23]
	v_mfma_f32_16x16x32_bf16 v[16:19], v[138:141], v[170:173], v[16:19]
	v_mfma_f32_16x16x32_bf16 v[4:7], v[130:133], v[162:165], v[4:7]
	v_mfma_f32_16x16x32_bf16 v[0:3], v[138:141], v[162:165], v[0:3]
	v_mfma_f32_16x16x32_bf16 v[52:55], v[134:137], v[190:193], v[52:55]
	v_mfma_f32_16x16x32_bf16 v[48:51], v[142:145], v[190:193], v[48:51]
	v_mfma_f32_16x16x32_bf16 v[36:39], v[134:137], v[182:185], v[36:39]
	v_mfma_f32_16x16x32_bf16 v[32:35], v[142:145], v[182:185], v[32:35]
	v_mfma_f32_16x16x32_bf16 v[20:23], v[134:137], v[174:177], v[20:23]
	v_mfma_f32_16x16x32_bf16 v[16:19], v[142:145], v[174:177], v[16:19]
	v_mfma_f32_16x16x32_bf16 v[4:7], v[134:137], v[166:169], v[4:7]
	v_mfma_f32_16x16x32_bf16 v[0:3], v[142:145], v[166:169], v[0:3]
	s_setprio 0
	s_branch .LBB0_165

; #define PG8_STAGE(bufoff, gbase, voff) do { _Pragma("unroll") for (int _i = 0; _i < 2; ++_i) \
;         __builtin_amdgcn_global_load_lds((const unsigned*)((const char*)(gbase) + (voff)[_i]), (PG8_LAS unsigned*)(lds + (bufoff) + ldsw + _i * 8192), 16, 0, 0); } while (0)
; #define PG8_LDA(dst, b, h) do { _Pragma("unroll") for (int m = 0; m < 4; ++m) _Pragma("unroll") for (int k = 0; k < 2; ++k) dst[m][k] = *(const PG8_LAS bf16x8*)(lds + PG8_SA(b, h) + aoff + m * 2048 + k * 1024); } while (0)
; #define PG8_LDB(dst, b, h) do { _Pragma("unroll") for (int n = 0; n < 2; ++n) _Pragma("unroll") for (int k = 0; k < 2; ++k) dst[n][k] = *(const PG8_LAS bf16x8*)(lds + PG8_SB(b, h) + boff + n * 2048 + k * 1024); } while (0)
; #define PG8_MMA(ai, bj, At, Bt) do { __builtin_amdgcn_s_setprio(1); _Pragma("unroll") for (int m = 0; m < 4; ++m) _Pragma("unroll") for (int n = 0; n < 2; ++n) _Pragma("unroll") for (int k = 0; k < 2; ++k) \
;         acc[ai][bj][m][n] = __builtin_amdgcn_mfma_f32_16x16x32_bf16(Bt[n][k], At[m][k], acc[ai][bj][m][n], 0, 0, 0); __builtin_amdgcn_s_setprio(0); } while (0)
; #define PG8_WAIT_V(n) asm volatile("s_waitcnt vmcnt(" #n ")" ::: "memory")
; #define PG8_BAR __builtin_amdgcn_s_barrier()
; template <class Epi, class Sched, bool ALIGN_EPI = false, bool SP2 = false>
; __device__ __forceinline__ void gemm_phase(PG8_LAS unsigned char* lds, const Gemm g, const Sched& S, const Epi& E) {
;     ...
;         for (int t = 0; t < ntu; t += 2) {
;             const bool last = (t == ntu - 2);
;             const char* a1 = cA + (size_t)(t + 1) * kstep;
;             const char* a2 = last ? nA : cA + (size_t)(t + 2) * kstep; const char* b2 = last ? nB : cB + (size_t)(t + 2) * kstep;
;             const char* a3 = a2 + kstep; const char* b3 = b2 + kstep;
;             if (last && has_next) S.a_ready(nxt);
;             if constexpr (SP2) {
;             PG8_LDB(B0, 0, 0); PG8_LDB(B1, 0, 1); PG8_SCHED; PG8_LDA(At, 0, 0); PG8_STAGE(PG8_SA(1, 1), a1 + hstep, voffA);
;             PG8_WAIT_V(8); PG8_WAIT_L(0); PG8_BAR; PG8_MMA(0, 0, At, B0); PG8_MMA(0, 1, At, B1); PG8_BAR; PG8_SCHED;
;             PG8_LDA(At, 0, 1); PG8_STAGE(PG8_SB(0, 0), b2, voffB); PG8_STAGE(PG8_SB(0, 1), b2 + hstep, voffB); PG8_STAGE(PG8_SA(0, 0), a2, voffA);
;             PG8_WAIT_V(8); PG8_WAIT_L(0); PG8_BAR; if (full) { PG8_MMA(1, 0, At, B0); PG8_MMA(1, 1, At, B1); } PG8_BAR; PG8_SCHED;
.LBB0_500:
	s_add_u32 s2, s80, 0xfffc0080
	s_addc_u32 s3, s81, -1
	s_add_i32 s4, 0, 0x10000
	s_cmp_eq_u32 s90, 12
	s_cselect_b32 s31, s1, s3
	s_cselect_b32 s30, s35, s2
	v_add_u32_e32 v128, s4, v226
	s_cselect_b32 s29, s51, s89
	s_cselect_b32 s28, s87, s88
	s_add_i32 s5, 0, 0x14000
	ds_read_b128 v[146:149], v128
	ds_read_b128 v[150:153], v128 offset:1024
	ds_read_b128 v[154:157], v128 offset:2048
	ds_read_b128 v[158:161], v128 offset:3072
	v_add_u32_e32 v128, s5, v226
	ds_read_b128 v[130:133], v128
	ds_read_b128 v[134:137], v128 offset:1024
	ds_read_b128 v[138:141], v128 offset:2048
	ds_read_b128 v[142:145], v128 offset:3072
	v_lshl_add_u64 v[196:197], s[80:81], 0, v[214:215]
	s_add_i32 m0, s65, 0xc000
	s_waitcnt lgkmcnt(7)
	ds_read_b128 v[162:165], v228
	ds_read_b128 v[166:169], v228 offset:1024
	ds_read_b128 v[170:173], v228 offset:2048
	ds_read_b128 v[174:177], v228 offset:3072
	ds_read_b128 v[178:181], v228 offset:4096
	ds_read_b128 v[182:185], v228 offset:5120
	ds_read_b128 v[186:189], v228 offset:6144
	ds_read_b128 v[190:193], v228 offset:7168
	global_load_lds_dwordx4 v[196:197], off
	v_lshl_add_u64 v[196:197], s[80:81], 0, v[216:217]
	s_add_i32 m0, s65, 0xe000
	s_nop 0
	global_load_lds_dwordx4 v[196:197], off
	s_waitcnt vmcnt(8)
	s_waitcnt lgkmcnt(0)
	s_barrier
	s_setprio 1
	v_mfma_f32_16x16x32_bf16 v[124:127], v[146:149], v[162:165], v[124:127]
	v_mfma_f32_16x16x32_bf16 v[120:123], v[154:157], v[162:165], v[120:123]
	v_mfma_f32_16x16x32_bf16 v[108:111], v[146:149], v[170:173], v[108:111]
	v_mfma_f32_16x16x32_bf16 v[104:107], v[154:157], v[170:173], v[104:107]
	v_mfma_f32_16x16x32_bf16 v[92:95], v[146:149], v[178:181], v[92:95]
	v_mfma_f32_16x16x32_bf16 v[88:91], v[154:157], v[178:181], v[88:91]
	v_mfma_f32_16x16x32_bf16 v[76:79], v[146:149], v[186:189], v[76:79]
	v_mfma_f32_16x16x32_bf16 v[72:75], v[154:157], v[186:189], v[72:75]
	v_mfma_f32_16x16x32_bf16 v[124:127], v[150:153], v[166:169], v[124:127]
	v_mfma_f32_16x16x32_bf16 v[120:123], v[158:161], v[166:169], v[120:123]
	v_mfma_f32_16x16x32_bf16 v[108:111], v[150:153], v[174:177], v[108:111]
	v_mfma_f32_16x16x32_bf16 v[104:107], v[158:161], v[174:177], v[104:107]
	v_mfma_f32_16x16x32_bf16 v[92:95], v[150:153], v[182:185], v[92:95]
	v_mfma_f32_16x16x32_bf16 v[88:91], v[158:161], v[182:185], v[88:91]
	v_mfma_f32_16x16x32_bf16 v[76:79], v[150:153], v[190:193], v[76:79]
	v_mfma_f32_16x16x32_bf16 v[72:75], v[158:161], v[190:193], v[72:75]
	v_mfma_f32_16x16x32_bf16 v[116:119], v[130:133], v[162:165], v[116:119]
	v_mfma_f32_16x16x32_bf16 v[112:115], v[138:141], v[162:165], v[112:115]
	v_mfma_f32_16x16x32_bf16 v[100:103], v[130:133], v[170:173], v[100:103]
	v_mfma_f32_16x16x32_bf16 v[96:99], v[138:141], v[170:173], v[96:99]
	v_mfma_f32_16x16x32_bf16 v[84:87], v[130:133], v[178:181], v[84:87]
	v_mfma_f32_16x16x32_bf16 v[80:83], v[138:141], v[178:181], v[80:83]
	v_mfma_f32_16x16x32_bf16 v[68:71], v[130:133], v[186:189], v[68:71]
	v_mfma_f32_16x16x32_bf16 v[64:67], v[138:141], v[186:189], v[64:67]
	v_mfma_f32_16x16x32_bf16 v[116:119], v[134:137], v[166:169], v[116:119]
	v_mfma_f32_16x16x32_bf16 v[112:115], v[142:145], v[166:169], v[112:115]
	v_mfma_f32_16x16x32_bf16 v[100:103], v[134:137], v[174:177], v[100:103]
	v_mfma_f32_16x16x32_bf16 v[96:99], v[142:145], v[174:177], v[96:99]
	v_mfma_f32_16x16x32_bf16 v[84:87], v[134:137], v[182:185], v[84:87]
	v_mfma_f32_16x16x32_bf16 v[80:83], v[142:145], v[182:185], v[80:83]
	v_mfma_f32_16x16x32_bf16 v[68:71], v[134:137], v[190:193], v[68:71]
	v_mfma_f32_16x16x32_bf16 v[64:67], v[142:145], v[190:193], v[64:67]
	s_setprio 0
	s_barrier
	s_add_i32 s2, s4, s64
	v_lshl_add_u64 v[218:219], s[28:29], 0, v[208:209]
	s_mov_b32 m0, s2
	ds_read_b128 v[186:189], v228 offset:16384
	ds_read_b128 v[190:193], v228 offset:17408
	ds_read_b128 v[178:181], v228 offset:18432
	ds_read_b128 v[182:185], v228 offset:19456
	ds_read_b128 v[170:173], v228 offset:20480
	ds_read_b128 v[174:177], v228 offset:21504
	ds_read_b128 v[162:165], v228 offset:22528
	ds_read_b128 v[166:169], v228 offset:23552
	global_load_lds_dwordx4 v[218:219], off
	s_add_i32 m0, s2, 0x2000
	s_add_u32 s2, s28, 0x40000
	v_lshl_add_u64 v[220:221], s[28:29], 0, v[212:213]
	s_addc_u32 s3, s29, 0
	s_add_i32 s4, s5, s64
	global_load_lds_dwordx4 v[220:221], off
	v_lshl_add_u64 v[196:197], s[2:3], 0, v[208:209]
	s_mov_b32 m0, s4
	v_lshl_add_u64 v[222:223], s[30:31], 0, v[206:207]
	global_load_lds_dwordx4 v[196:197], off
	v_lshl_add_u64 v[196:197], s[2:3], 0, v[212:213]
	s_add_i32 m0, s4, 0x2000
	v_lshl_add_u64 v[224:225], s[30:31], 0, v[210:211]
	global_load_lds_dwordx4 v[196:197], off
	s_mov_b32 m0, s65
	v_cndmask_b32_e64 v128, 0, 1, s[78:79]
	global_load_lds_dwordx4 v[222:223], off
	s_mov_b32 m0, s70
	v_cmp_ne_u32_e64 s[38:39], 1, v128
	global_load_lds_dwordx4 v[224:225], off
	s_waitcnt vmcnt(8)
	s_waitcnt lgkmcnt(0)
	s_andn2_b64 vcc, exec, s[78:79]
	s_barrier
	s_cbranch_vccnz .LBB0_502
; #define PG8_MMA(ai, bj, At, Bt) do { __builtin_amdgcn_s_setprio(1); _Pragma("unroll") for (int m = 0; m < 4; ++m) _Pragma("unroll") for (int n = 0; n < 2; ++n) _Pragma("unroll") for (int k = 0; k < 2; ++k) \
;         acc[ai][bj][m][n] = __builtin_amdgcn_mfma_f32_16x16x32_bf16(Bt[n][k], At[m][k], acc[ai][bj][m][n], 0, 0, 0); __builtin_amdgcn_s_setprio(0); } while (0)
; #define PG8_WAIT_V(n) asm volatile("s_waitcnt vmcnt(" #n ")" ::: "memory")
; #define PG8_WAIT_L(n) asm volatile("s_waitcnt lgkmcnt(" #n ")" ::: "memory")
; #define PG8_BAR __builtin_amdgcn_s_barrier()
; #define PG8_SCHED __builtin_amdgcn_sched_barrier(0)
; template <class Epi, class Sched, bool ALIGN_EPI = false, bool SP2 = false>
; __device__ __forceinline__ void gemm_phase(PG8_LAS unsigned char* lds, const Gemm g, const Sched& S, const Epi& E) {
;     ...
;             PG8_WAIT_V(8); PG8_WAIT_L(0); PG8_BAR; if (full) { PG8_MMA(1, 0, At, B0); PG8_MMA(1, 1, At, B1); } PG8_BAR; PG8_SCHED;
	s_setprio 1
	v_mfma_f32_16x16x32_bf16 v[60:63], v[146:149], v[186:189], v[60:63]
	v_mfma_f32_16x16x32_bf16 v[56:59], v[154:157], v[186:189], v[56:59]
	v_mfma_f32_16x16x32_bf16 v[44:47], v[146:149], v[178:181], v[44:47]
	v_mfma_f32_16x16x32_bf16 v[40:43], v[154:157], v[178:181], v[40:43]
	v_mfma_f32_16x16x32_bf16 v[28:31], v[146:149], v[170:173], v[28:31]
	v_mfma_f32_16x16x32_bf16 v[24:27], v[154:157], v[170:173], v[24:27]
	v_mfma_f32_16x16x32_bf16 v[12:15], v[146:149], v[162:165], v[12:15]
	v_mfma_f32_16x16x32_bf16 v[8:11], v[154:157], v[162:165], v[8:11]
	v_mfma_f32_16x16x32_bf16 v[60:63], v[150:153], v[190:193], v[60:63]
	v_mfma_f32_16x16x32_bf16 v[56:59], v[158:161], v[190:193], v[56:59]
	v_mfma_f32_16x16x32_bf16 v[44:47], v[150:153], v[182:185], v[44:47]
	v_mfma_f32_16x16x32_bf16 v[40:43], v[158:161], v[182:185], v[40:43]
	v_mfma_f32_16x16x32_bf16 v[28:31], v[150:153], v[174:177], v[28:31]
	v_mfma_f32_16x16x32_bf16 v[24:27], v[158:161], v[174:177], v[24:27]
	v_mfma_f32_16x16x32_bf16 v[12:15], v[150:153], v[166:169], v[12:15]
	v_mfma_f32_16x16x32_bf16 v[8:11], v[158:161], v[166:169], v[8:11]
	v_mfma_f32_16x16x32_bf16 v[52:55], v[130:133], v[186:189], v[52:55]
	v_mfma_f32_16x16x32_bf16 v[48:51], v[138:141], v[186:189], v[48:51]
	v_mfma_f32_16x16x32_bf16 v[36:39], v[130:133], v[178:181], v[36:39]
	v_mfma_f32_16x16x32_bf16 v[32:35], v[138:141], v[178:181], v[32:35]
	v_mfma_f32_16x16x32_bf16 v[20:23], v[130:133], v[170:173], v[20:23]
	v_mfma_f32_16x16x32_bf16 v[16:19], v[138:141], v[170:173], v[16:19]
	v_mfma_f32_16x16x32_bf16 v[4:7], v[130:133], v[162:165], v[4:7]
	v_mfma_f32_16x16x32_bf16 v[0:3], v[138:141], v[162:165], v[0:3]
	v_mfma_f32_16x16x32_bf16 v[52:55], v[134:137], v[190:193], v[52:55]
	v_mfma_f32_16x16x32_bf16 v[48:51], v[142:145], v[190:193], v[48:51]
	v_mfma_f32_16x16x32_bf16 v[36:39], v[134:137], v[182:185], v[36:39]
	v_mfma_f32_16x16x32_bf16 v[32:35], v[142:145], v[182:185], v[32:35]
	v_mfma_f32_16x16x32_bf16 v[20:23], v[134:137], v[174:177], v[20:23]
	v_mfma_f32_16x16x32_bf16 v[16:19], v[142:145], v[174:177], v[16:19]
	v_mfma_f32_16x16x32_bf16 v[4:7], v[134:137], v[166:169], v[4:7]
	v_mfma_f32_16x16x32_bf16 v[0:3], v[142:145], v[166:169], v[0:3]
	s_setprio 0
; #define PG8_STAGE(bufoff, gbase, voff) do { _Pragma("unroll") for (int _i = 0; _i < 2; ++_i) \
;         __builtin_amdgcn_global_load_lds((const unsigned*)((const char*)(gbase) + (voff)[_i]), (PG8_LAS unsigned*)(lds + (bufoff) + ldsw + _i * 8192), 16, 0, 0); } while (0)
; #define PG8_LDA(dst, b, h) do { _Pragma("unroll") for (int m = 0; m < 4; ++m) _Pragma("unroll") for (int k = 0; k < 2; ++k) dst[m][k] = *(const PG8_LAS bf16x8*)(lds + PG8_SA(b, h) + aoff + m * 2048 + k * 1024); } while (0)
; #define PG8_LDB(dst, b, h) do { _Pragma("unroll") for (int n = 0; n < 2; ++n) _Pragma("unroll") for (int k = 0; k < 2; ++k) dst[n][k] = *(const PG8_LAS bf16x8*)(lds + PG8_SB(b, h) + boff + n * 2048 + k * 1024); } while (0)
; #define PG8_MMA(ai, bj, At, Bt) do { __builtin_amdgcn_s_setprio(1); _Pragma("unroll") for (int m = 0; m < 4; ++m) _Pragma("unroll") for (int n = 0; n < 2; ++n) _Pragma("unroll") for (int k = 0; k < 2; ++k) \
;         acc[ai][bj][m][n] = __builtin_amdgcn_mfma_f32_16x16x32_bf16(Bt[n][k], At[m][k], acc[ai][bj][m][n], 0, 0, 0); __builtin_amdgcn_s_setprio(0); } while (0)
; #define PG8_WAIT_V(n) asm volatile("s_waitcnt vmcnt(" #n ")" ::: "memory")
; #define PG8_WAIT_L(n) asm volatile("s_waitcnt lgkmcnt(" #n ")" ::: "memory")
; #define PG8_BAR __builtin_amdgcn_s_barrier()
; #define PG8_SCHED __builtin_amdgcn_sched_barrier(0)
; template <class Epi, class Sched, bool ALIGN_EPI = false, bool SP2 = false>
; __device__ __forceinline__ void gemm_phase(PG8_LAS unsigned char* lds, const Gemm g, const Sched& S, const Epi& E) {
;     ...
;             PG8_LDB(B0, 1, 0); PG8_LDB(B1, 1, 1); PG8_SCHED; PG8_LDA(At, 1, 0); PG8_STAGE(PG8_SA(0, 1), a2 + hstep, voffA);
;             PG8_WAIT_V(8); PG8_WAIT_L(0); PG8_BAR; PG8_MMA(0, 0, At, B0); PG8_MMA(0, 1, At, B1); PG8_BAR; PG8_SCHED;
;             PG8_LDA(At, 1, 1); PG8_STAGE(PG8_SB(1, 0), b3, voffB); PG8_STAGE(PG8_SB(1, 1), b3 + hstep, voffB); PG8_STAGE(PG8_SA(1, 0), a3, voffA);
;             PG8_WAIT_V(8); PG8_WAIT_L(0); PG8_BAR; if (full) { PG8_MMA(1, 0, At, B0); PG8_MMA(1, 1, At, B1); } PG8_BAR; PG8_SCHED;
.LBB0_502:
	s_barrier
	s_add_i32 s4, 0, 0x18000
	v_add_u32_e32 v128, s4, v226
	s_add_i32 s5, 0, 0x1c000
	ds_read_b128 v[146:149], v128
	ds_read_b128 v[150:153], v128 offset:1024
	ds_read_b128 v[154:157], v128 offset:2048
	ds_read_b128 v[158:161], v128 offset:3072
	v_add_u32_e32 v128, s5, v226
	ds_read_b128 v[130:133], v128
	ds_read_b128 v[134:137], v128 offset:1024
	ds_read_b128 v[138:141], v128 offset:2048
	ds_read_b128 v[142:145], v128 offset:3072
	s_add_u32 s2, s30, 0x40000
	s_addc_u32 s3, s31, 0
	s_mov_b32 m0, s71
	v_lshl_add_u64 v[196:197], s[2:3], 0, v[206:207]
	s_waitcnt lgkmcnt(7)
	ds_read_b128 v[162:165], v228 offset:32768
	ds_read_b128 v[166:169], v228 offset:33792
	ds_read_b128 v[170:173], v228 offset:34816
	ds_read_b128 v[174:177], v228 offset:35840
	ds_read_b128 v[178:181], v228 offset:36864
	ds_read_b128 v[182:185], v228 offset:37888
	ds_read_b128 v[186:189], v228 offset:38912
	ds_read_b128 v[190:193], v228 offset:39936
	global_load_lds_dwordx4 v[196:197], off
	v_lshl_add_u64 v[196:197], s[2:3], 0, v[210:211]
	s_mov_b32 m0, s77
	s_nop 0
	global_load_lds_dwordx4 v[196:197], off
	s_waitcnt vmcnt(8)
	s_waitcnt lgkmcnt(0)
	s_barrier
	s_setprio 1
	v_mfma_f32_16x16x32_bf16 v[124:127], v[146:149], v[162:165], v[124:127]
	v_mfma_f32_16x16x32_bf16 v[120:123], v[154:157], v[162:165], v[120:123]
	v_mfma_f32_16x16x32_bf16 v[108:111], v[146:149], v[170:173], v[108:111]
	v_mfma_f32_16x16x32_bf16 v[104:107], v[154:157], v[170:173], v[104:107]
	v_mfma_f32_16x16x32_bf16 v[92:95], v[146:149], v[178:181], v[92:95]
	v_mfma_f32_16x16x32_bf16 v[88:91], v[154:157], v[178:181], v[88:91]
	v_mfma_f32_16x16x32_bf16 v[76:79], v[146:149], v[186:189], v[76:79]
	v_mfma_f32_16x16x32_bf16 v[72:75], v[154:157], v[186:189], v[72:75]
	v_mfma_f32_16x16x32_bf16 v[124:127], v[150:153], v[166:169], v[124:127]
	v_mfma_f32_16x16x32_bf16 v[120:123], v[158:161], v[166:169], v[120:123]
	v_mfma_f32_16x16x32_bf16 v[108:111], v[150:153], v[174:177], v[108:111]
	v_mfma_f32_16x16x32_bf16 v[104:107], v[158:161], v[174:177], v[104:107]
	v_mfma_f32_16x16x32_bf16 v[92:95], v[150:153], v[182:185], v[92:95]
	v_mfma_f32_16x16x32_bf16 v[88:91], v[158:161], v[182:185], v[88:91]
	v_mfma_f32_16x16x32_bf16 v[76:79], v[150:153], v[190:193], v[76:79]
	v_mfma_f32_16x16x32_bf16 v[72:75], v[158:161], v[190:193], v[72:75]
	v_mfma_f32_16x16x32_bf16 v[116:119], v[130:133], v[162:165], v[116:119]
	v_mfma_f32_16x16x32_bf16 v[112:115], v[138:141], v[162:165], v[112:115]
	v_mfma_f32_16x16x32_bf16 v[100:103], v[130:133], v[170:173], v[100:103]
	v_mfma_f32_16x16x32_bf16 v[96:99], v[138:141], v[170:173], v[96:99]
	v_mfma_f32_16x16x32_bf16 v[84:87], v[130:133], v[178:181], v[84:87]
	v_mfma_f32_16x16x32_bf16 v[80:83], v[138:141], v[178:181], v[80:83]
	v_mfma_f32_16x16x32_bf16 v[68:71], v[130:133], v[186:189], v[68:71]
	v_mfma_f32_16x16x32_bf16 v[64:67], v[138:141], v[186:189], v[64:67]
	v_mfma_f32_16x16x32_bf16 v[116:119], v[134:137], v[166:169], v[116:119]
	v_mfma_f32_16x16x32_bf16 v[112:115], v[142:145], v[166:169], v[112:115]
	v_mfma_f32_16x16x32_bf16 v[100:103], v[134:137], v[174:177], v[100:103]
	v_mfma_f32_16x16x32_bf16 v[96:99], v[142:145], v[174:177], v[96:99]
	v_mfma_f32_16x16x32_bf16 v[84:87], v[134:137], v[182:185], v[84:87]
	v_mfma_f32_16x16x32_bf16 v[80:83], v[142:145], v[182:185], v[80:83]
	v_mfma_f32_16x16x32_bf16 v[68:71], v[134:137], v[190:193], v[68:71]
	v_mfma_f32_16x16x32_bf16 v[64:67], v[142:145], v[190:193], v[64:67]
	s_setprio 0
	s_barrier
	s_add_i32 s2, s4, s64
	v_lshl_add_u64 v[196:197], v[218:219], 0, s[26:27]
	s_mov_b32 m0, s2
	ds_read_b128 v[186:189], v228 offset:49152
	ds_read_b128 v[190:193], v228 offset:50176
	ds_read_b128 v[178:181], v228 offset:51200
	ds_read_b128 v[182:185], v228 offset:52224
	ds_read_b128 v[170:173], v228 offset:53248
	ds_read_b128 v[174:177], v228 offset:54272
	ds_read_b128 v[162:165], v228 offset:55296
	ds_read_b128 v[166:169], v228 offset:56320
	global_load_lds_dwordx4 v[196:197], off
	s_add_i32 m0, s2, 0x2000
	s_add_u32 s2, s28, 0x40080
	v_lshl_add_u64 v[196:197], v[220:221], 0, s[26:27]
	s_addc_u32 s3, s29, 0
	s_add_i32 s4, s5, s64
	global_load_lds_dwordx4 v[196:197], off
	v_lshl_add_u64 v[196:197], s[2:3], 0, v[208:209]
	s_mov_b32 m0, s4
	s_and_b64 vcc, exec, s[38:39]
	global_load_lds_dwordx4 v[196:197], off
	v_lshl_add_u64 v[196:197], s[2:3], 0, v[212:213]
	s_add_i32 m0, s4, 0x2000
	s_nop 0
	global_load_lds_dwordx4 v[196:197], off
	v_lshl_add_u64 v[196:197], v[222:223], 0, s[26:27]
	s_mov_b32 m0, s82
	s_nop 0
	global_load_lds_dwordx4 v[196:197], off
	v_lshl_add_u64 v[196:197], v[224:225], 0, s[26:27]
	s_mov_b32 m0, s83
	s_nop 0
	global_load_lds_dwordx4 v[196:197], off
	s_waitcnt vmcnt(8)
	s_waitcnt lgkmcnt(0)
	s_barrier
	s_cbranch_vccnz .LBB0_499
	s_setprio 1
	v_mfma_f32_16x16x32_bf16 v[60:63], v[146:149], v[186:189], v[60:63]
	v_mfma_f32_16x16x32_bf16 v[56:59], v[154:157], v[186:189], v[56:59]
	v_mfma_f32_16x16x32_bf16 v[44:47], v[146:149], v[178:181], v[44:47]
	v_mfma_f32_16x16x32_bf16 v[40:43], v[154:157], v[178:181], v[40:43]
	v_mfma_f32_16x16x32_bf16 v[28:31], v[146:149], v[170:173], v[28:31]
	v_mfma_f32_16x16x32_bf16 v[24:27], v[154:157], v[170:173], v[24:27]
	v_mfma_f32_16x16x32_bf16 v[12:15], v[146:149], v[162:165], v[12:15]
	v_mfma_f32_16x16x32_bf16 v[8:11], v[154:157], v[162:165], v[8:11]
	v_mfma_f32_16x16x32_bf16 v[60:63], v[150:153], v[190:193], v[60:63]
	v_mfma_f32_16x16x32_bf16 v[56:59], v[158:161], v[190:193], v[56:59]
	v_mfma_f32_16x16x32_bf16 v[44:47], v[150:153], v[182:185], v[44:47]
	v_mfma_f32_16x16x32_bf16 v[40:43], v[158:161], v[182:185], v[40:43]
	v_mfma_f32_16x16x32_bf16 v[28:31], v[150:153], v[174:177], v[28:31]
	v_mfma_f32_16x16x32_bf16 v[24:27], v[158:161], v[174:177], v[24:27]
	v_mfma_f32_16x16x32_bf16 v[12:15], v[150:153], v[166:169], v[12:15]
	v_mfma_f32_16x16x32_bf16 v[8:11], v[158:161], v[166:169], v[8:11]
	v_mfma_f32_16x16x32_bf16 v[52:55], v[130:133], v[186:189], v[52:55]
	v_mfma_f32_16x16x32_bf16 v[48:51], v[138:141], v[186:189], v[48:51]
	v_mfma_f32_16x16x32_bf16 v[36:39], v[130:133], v[178:181], v[36:39]
	v_mfma_f32_16x16x32_bf16 v[32:35], v[138:141], v[178:181], v[32:35]
	v_mfma_f32_16x16x32_bf16 v[20:23], v[130:133], v[170:173], v[20:23]
	v_mfma_f32_16x16x32_bf16 v[16:19], v[138:141], v[170:173], v[16:19]
	v_mfma_f32_16x16x32_bf16 v[4:7], v[130:133], v[162:165], v[4:7]
	v_mfma_f32_16x16x32_bf16 v[0:3], v[138:141], v[162:165], v[0:3]
	v_mfma_f32_16x16x32_bf16 v[52:55], v[134:137], v[190:193], v[52:55]
	v_mfma_f32_16x16x32_bf16 v[48:51], v[142:145], v[190:193], v[48:51]
	v_mfma_f32_16x16x32_bf16 v[36:39], v[134:137], v[182:185], v[36:39]
	v_mfma_f32_16x16x32_bf16 v[32:35], v[142:145], v[182:185], v[32:35]
	v_mfma_f32_16x16x32_bf16 v[20:23], v[134:137], v[174:177], v[20:23]
	v_mfma_f32_16x16x32_bf16 v[16:19], v[142:145], v[174:177], v[16:19]
	v_mfma_f32_16x16x32_bf16 v[4:7], v[134:137], v[166:169], v[4:7]
	v_mfma_f32_16x16x32_bf16 v[0:3], v[142:145], v[166:169], v[0:3]
	s_setprio 0
	s_branch .LBB0_499

; #define PG8_STAGE(bufoff, gbase, voff) do { _Pragma("unroll") for (int _i = 0; _i < 2; ++_i) \
;         __builtin_amdgcn_global_load_lds((const unsigned*)((const char*)(gbase) + (voff)[_i]), (PG8_LAS unsigned*)(lds + (bufoff) + ldsw + _i * 8192), 16, 0, 0); } while (0)
; #define PG8_LDA(dst, b, h) do { _Pragma("unroll") for (int m = 0; m < 4; ++m) _Pragma("unroll") for (int k = 0; k < 2; ++k) dst[m][k] = *(const PG8_LAS bf16x8*)(lds + PG8_SA(b, h) + aoff + m * 2048 + k * 1024); } while (0)
; #define PG8_LDB(dst, b, h) do { _Pragma("unroll") for (int n = 0; n < 2; ++n) _Pragma("unroll") for (int k = 0; k < 2; ++k) dst[n][k] = *(const PG8_LAS bf16x8*)(lds + PG8_SB(b, h) + boff + n * 2048 + k * 1024); } while (0)
; #define PG8_MMA(ai, bj, At, Bt) do { __builtin_amdgcn_s_setprio(1); _Pragma("unroll") for (int m = 0; m < 4; ++m) _Pragma("unroll") for (int n = 0; n < 2; ++n) _Pragma("unroll") for (int k = 0; k < 2; ++k) \
;         acc[ai][bj][m][n] = __builtin_amdgcn_mfma_f32_16x16x32_bf16(Bt[n][k], At[m][k], acc[ai][bj][m][n], 0, 0, 0); __builtin_amdgcn_s_setprio(0); } while (0)
; #define PG8_WAIT_V(n) asm volatile("s_waitcnt vmcnt(" #n ")" ::: "memory")
; #define PG8_BAR __builtin_amdgcn_s_barrier()
; template <class Epi, class Sched, bool ALIGN_EPI = false, bool SP2 = false>
; __device__ __forceinline__ void gemm_phase(PG8_LAS unsigned char* lds, const Gemm g, const Sched& S, const Epi& E) {
;     ...
;         for (int t = 0; t < ntu; t += 2) {
;             const bool last = (t == ntu - 2);
;             const char* a1 = cA + (size_t)(t + 1) * kstep;
;             const char* a2 = last ? nA : cA + (size_t)(t + 2) * kstep; const char* b2 = last ? nB : cB + (size_t)(t + 2) * kstep;
;             const char* a3 = a2 + kstep; const char* b3 = b2 + kstep;
;             if (last && has_next) S.a_ready(nxt);
;             if constexpr (SP2) {
;             PG8_LDB(B0, 0, 0); PG8_LDB(B1, 0, 1); PG8_SCHED; PG8_LDA(At, 0, 0); PG8_STAGE(PG8_SA(1, 1), a1 + hstep, voffA);
;             PG8_WAIT_V(8); PG8_WAIT_L(0); PG8_BAR; PG8_MMA(0, 0, At, B0); PG8_MMA(0, 1, At, B1); PG8_BAR; PG8_SCHED;
;             PG8_LDA(At, 0, 1); PG8_STAGE(PG8_SB(0, 0), b2, voffB); PG8_STAGE(PG8_SB(0, 1), b2 + hstep, voffB); PG8_STAGE(PG8_SA(0, 0), a2, voffA);
;             PG8_WAIT_V(8); PG8_WAIT_L(0); PG8_BAR; if (full) { PG8_MMA(1, 0, At, B0); PG8_MMA(1, 1, At, B1); } PG8_BAR; PG8_SCHED;
.LBB0_916:
	s_add_u32 s2, s48, 0xfffc0080
	s_addc_u32 s3, s49, -1
	s_add_i32 s4, 0, 0x10000
	s_cmp_eq_u32 s79, s51
	s_cselect_b32 s35, s85, s3
	s_cselect_b32 s34, s84, s2
	v_add_u32_e32 v128, s4, v195
	s_cselect_b32 s29, s87, s50
	s_cselect_b32 s28, s86, s83
	s_add_i32 s5, 0, 0x14000
	ds_read_b128 v[146:149], v128
	ds_read_b128 v[150:153], v128 offset:1024
	ds_read_b128 v[154:157], v128 offset:2048
	ds_read_b128 v[158:161], v128 offset:3072
	v_add_u32_e32 v128, s5, v195
	ds_read_b128 v[130:133], v128
	ds_read_b128 v[134:137], v128 offset:1024
	ds_read_b128 v[138:141], v128 offset:2048
	ds_read_b128 v[142:145], v128 offset:3072
	v_lshl_add_u64 v[196:197], s[48:49], 0, v[218:219]
	s_add_i32 m0, s70, 0xc000
	s_waitcnt lgkmcnt(7)
	ds_read_b128 v[162:165], v242
	ds_read_b128 v[166:169], v242 offset:1024
	ds_read_b128 v[170:173], v242 offset:2048
	ds_read_b128 v[174:177], v242 offset:3072
	ds_read_b128 v[178:181], v242 offset:4096
	ds_read_b128 v[182:185], v242 offset:5120
	ds_read_b128 v[186:189], v242 offset:6144
	ds_read_b128 v[190:193], v242 offset:7168
	global_load_lds_dwordx4 v[196:197], off
	v_lshl_add_u64 v[196:197], s[48:49], 0, v[220:221]
	s_add_i32 m0, s70, 0xe000
	s_nop 0
	global_load_lds_dwordx4 v[196:197], off
	s_waitcnt vmcnt(8)
	s_waitcnt lgkmcnt(0)
	s_barrier
	s_setprio 1
	v_mfma_f32_16x16x32_bf16 v[124:127], v[146:149], v[162:165], v[124:127]
	v_mfma_f32_16x16x32_bf16 v[120:123], v[154:157], v[162:165], v[120:123]
	v_mfma_f32_16x16x32_bf16 v[116:119], v[146:149], v[170:173], v[116:119]
	v_mfma_f32_16x16x32_bf16 v[112:115], v[154:157], v[170:173], v[112:115]
	v_mfma_f32_16x16x32_bf16 v[104:107], v[146:149], v[178:181], v[104:107]
	v_mfma_f32_16x16x32_bf16 v[96:99], v[154:157], v[178:181], v[96:99]
	v_mfma_f32_16x16x32_bf16 v[88:91], v[146:149], v[186:189], v[88:91]
	v_mfma_f32_16x16x32_bf16 v[80:83], v[154:157], v[186:189], v[80:83]
	v_mfma_f32_16x16x32_bf16 v[124:127], v[150:153], v[166:169], v[124:127]
	v_mfma_f32_16x16x32_bf16 v[120:123], v[158:161], v[166:169], v[120:123]
	v_mfma_f32_16x16x32_bf16 v[116:119], v[150:153], v[174:177], v[116:119]
	v_mfma_f32_16x16x32_bf16 v[112:115], v[158:161], v[174:177], v[112:115]
	v_mfma_f32_16x16x32_bf16 v[104:107], v[150:153], v[182:185], v[104:107]
	v_mfma_f32_16x16x32_bf16 v[96:99], v[158:161], v[182:185], v[96:99]
	v_mfma_f32_16x16x32_bf16 v[88:91], v[150:153], v[190:193], v[88:91]
	v_mfma_f32_16x16x32_bf16 v[80:83], v[158:161], v[190:193], v[80:83]
	v_mfma_f32_16x16x32_bf16 v[108:111], v[130:133], v[162:165], v[108:111]
	v_mfma_f32_16x16x32_bf16 v[100:103], v[138:141], v[162:165], v[100:103]
	v_mfma_f32_16x16x32_bf16 v[92:95], v[130:133], v[170:173], v[92:95]
	v_mfma_f32_16x16x32_bf16 v[84:87], v[138:141], v[170:173], v[84:87]
	v_mfma_f32_16x16x32_bf16 v[76:79], v[130:133], v[178:181], v[76:79]
	v_mfma_f32_16x16x32_bf16 v[72:75], v[138:141], v[178:181], v[72:75]
	v_mfma_f32_16x16x32_bf16 v[68:71], v[130:133], v[186:189], v[68:71]
	v_mfma_f32_16x16x32_bf16 v[56:59], v[138:141], v[186:189], v[56:59]
	v_mfma_f32_16x16x32_bf16 v[108:111], v[134:137], v[166:169], v[108:111]
	v_mfma_f32_16x16x32_bf16 v[100:103], v[142:145], v[166:169], v[100:103]
	v_mfma_f32_16x16x32_bf16 v[92:95], v[134:137], v[174:177], v[92:95]
	v_mfma_f32_16x16x32_bf16 v[84:87], v[142:145], v[174:177], v[84:87]
	v_mfma_f32_16x16x32_bf16 v[76:79], v[134:137], v[182:185], v[76:79]
	v_mfma_f32_16x16x32_bf16 v[72:75], v[142:145], v[182:185], v[72:75]
	v_mfma_f32_16x16x32_bf16 v[68:71], v[134:137], v[190:193], v[68:71]
	v_mfma_f32_16x16x32_bf16 v[56:59], v[142:145], v[190:193], v[56:59]
	s_setprio 0
	s_barrier
	s_add_i32 s2, s4, s65
	v_lshl_add_u64 v[222:223], s[28:29], 0, v[208:209]
	s_mov_b32 m0, s2
	ds_read_b128 v[186:189], v242 offset:16384
	ds_read_b128 v[190:193], v242 offset:17408
	ds_read_b128 v[178:181], v242 offset:18432
	ds_read_b128 v[182:185], v242 offset:19456
	ds_read_b128 v[170:173], v242 offset:20480
	ds_read_b128 v[174:177], v242 offset:21504
	ds_read_b128 v[162:165], v242 offset:22528
	ds_read_b128 v[166:169], v242 offset:23552
	global_load_lds_dwordx4 v[222:223], off
	s_add_i32 m0, s2, 0x2000
	s_add_u32 s2, s28, 0x40000
	v_lshl_add_u64 v[224:225], s[28:29], 0, v[212:213]
	s_addc_u32 s3, s29, 0
	s_add_i32 s4, s5, s65
	global_load_lds_dwordx4 v[224:225], off
	v_lshl_add_u64 v[196:197], s[2:3], 0, v[208:209]
	s_mov_b32 m0, s4
	v_lshl_add_u64 v[226:227], s[34:35], 0, v[206:207]
	global_load_lds_dwordx4 v[196:197], off
	v_lshl_add_u64 v[196:197], s[2:3], 0, v[212:213]
	s_add_i32 m0, s4, 0x2000
	v_lshl_add_u64 v[228:229], s[34:35], 0, v[210:211]
	global_load_lds_dwordx4 v[196:197], off
	s_mov_b32 m0, s70
	v_cndmask_b32_e64 v128, 0, 1, s[92:93]
	global_load_lds_dwordx4 v[226:227], off
	s_mov_b32 m0, s71
	v_cmp_ne_u32_e64 s[38:39], 1, v128
	global_load_lds_dwordx4 v[228:229], off
	s_waitcnt vmcnt(8)
	s_waitcnt lgkmcnt(0)
	s_andn2_b64 vcc, exec, s[92:93]
	s_barrier
	s_cbranch_vccnz .LBB0_918
; #define PG8_MMA(ai, bj, At, Bt) do { __builtin_amdgcn_s_setprio(1); _Pragma("unroll") for (int m = 0; m < 4; ++m) _Pragma("unroll") for (int n = 0; n < 2; ++n) _Pragma("unroll") for (int k = 0; k < 2; ++k) \
;         acc[ai][bj][m][n] = __builtin_amdgcn_mfma_f32_16x16x32_bf16(Bt[n][k], At[m][k], acc[ai][bj][m][n], 0, 0, 0); __builtin_amdgcn_s_setprio(0); } while (0)
; #define PG8_WAIT_V(n) asm volatile("s_waitcnt vmcnt(" #n ")" ::: "memory")
; #define PG8_WAIT_L(n) asm volatile("s_waitcnt lgkmcnt(" #n ")" ::: "memory")
; #define PG8_BAR __builtin_amdgcn_s_barrier()
; #define PG8_SCHED __builtin_amdgcn_sched_barrier(0)
; template <class Epi, class Sched, bool ALIGN_EPI = false, bool SP2 = false>
; __device__ __forceinline__ void gemm_phase(PG8_LAS unsigned char* lds, const Gemm g, const Sched& S, const Epi& E) {
;     ...
;             PG8_WAIT_V(8); PG8_WAIT_L(0); PG8_BAR; if (full) { PG8_MMA(1, 0, At, B0); PG8_MMA(1, 1, At, B1); } PG8_BAR; PG8_SCHED;
	s_setprio 1
	v_mfma_f32_16x16x32_bf16 v[64:67], v[146:149], v[186:189], v[64:67]
	v_mfma_f32_16x16x32_bf16 v[60:63], v[154:157], v[186:189], v[60:63]
	v_mfma_f32_16x16x32_bf16 v[44:47], v[146:149], v[178:181], v[44:47]
	v_mfma_f32_16x16x32_bf16 v[40:43], v[154:157], v[178:181], v[40:43]
	v_mfma_f32_16x16x32_bf16 v[28:31], v[146:149], v[170:173], v[28:31]
	v_mfma_f32_16x16x32_bf16 v[24:27], v[154:157], v[170:173], v[24:27]
	v_mfma_f32_16x16x32_bf16 v[12:15], v[146:149], v[162:165], v[12:15]
	v_mfma_f32_16x16x32_bf16 v[8:11], v[154:157], v[162:165], v[8:11]
	v_mfma_f32_16x16x32_bf16 v[64:67], v[150:153], v[190:193], v[64:67]
	v_mfma_f32_16x16x32_bf16 v[60:63], v[158:161], v[190:193], v[60:63]
	v_mfma_f32_16x16x32_bf16 v[44:47], v[150:153], v[182:185], v[44:47]
	v_mfma_f32_16x16x32_bf16 v[40:43], v[158:161], v[182:185], v[40:43]
	v_mfma_f32_16x16x32_bf16 v[28:31], v[150:153], v[174:177], v[28:31]
	v_mfma_f32_16x16x32_bf16 v[24:27], v[158:161], v[174:177], v[24:27]
	v_mfma_f32_16x16x32_bf16 v[12:15], v[150:153], v[166:169], v[12:15]
	v_mfma_f32_16x16x32_bf16 v[8:11], v[158:161], v[166:169], v[8:11]
	v_mfma_f32_16x16x32_bf16 v[52:55], v[130:133], v[186:189], v[52:55]
	v_mfma_f32_16x16x32_bf16 v[48:51], v[138:141], v[186:189], v[48:51]
	v_mfma_f32_16x16x32_bf16 v[36:39], v[130:133], v[178:181], v[36:39]
	v_mfma_f32_16x16x32_bf16 v[32:35], v[138:141], v[178:181], v[32:35]
	v_mfma_f32_16x16x32_bf16 v[20:23], v[130:133], v[170:173], v[20:23]
	v_mfma_f32_16x16x32_bf16 v[16:19], v[138:141], v[170:173], v[16:19]
	v_mfma_f32_16x16x32_bf16 v[4:7], v[130:133], v[162:165], v[4:7]
	v_mfma_f32_16x16x32_bf16 v[0:3], v[138:141], v[162:165], v[0:3]
	v_mfma_f32_16x16x32_bf16 v[52:55], v[134:137], v[190:193], v[52:55]
	v_mfma_f32_16x16x32_bf16 v[48:51], v[142:145], v[190:193], v[48:51]
	v_mfma_f32_16x16x32_bf16 v[36:39], v[134:137], v[182:185], v[36:39]
	v_mfma_f32_16x16x32_bf16 v[32:35], v[142:145], v[182:185], v[32:35]
	v_mfma_f32_16x16x32_bf16 v[20:23], v[134:137], v[174:177], v[20:23]
	v_mfma_f32_16x16x32_bf16 v[16:19], v[142:145], v[174:177], v[16:19]
	v_mfma_f32_16x16x32_bf16 v[4:7], v[134:137], v[166:169], v[4:7]
	v_mfma_f32_16x16x32_bf16 v[0:3], v[142:145], v[166:169], v[0:3]
	s_setprio 0
; #define PG8_STAGE(bufoff, gbase, voff) do { _Pragma("unroll") for (int _i = 0; _i < 2; ++_i) \
;         __builtin_amdgcn_global_load_lds((const unsigned*)((const char*)(gbase) + (voff)[_i]), (PG8_LAS unsigned*)(lds + (bufoff) + ldsw + _i * 8192), 16, 0, 0); } while (0)
; #define PG8_LDA(dst, b, h) do { _Pragma("unroll") for (int m = 0; m < 4; ++m) _Pragma("unroll") for (int k = 0; k < 2; ++k) dst[m][k] = *(const PG8_LAS bf16x8*)(lds + PG8_SA(b, h) + aoff + m * 2048 + k * 1024); } while (0)
; #define PG8_LDB(dst, b, h) do { _Pragma("unroll") for (int n = 0; n < 2; ++n) _Pragma("unroll") for (int k = 0; k < 2; ++k) dst[n][k] = *(const PG8_LAS bf16x8*)(lds + PG8_SB(b, h) + boff + n * 2048 + k * 1024); } while (0)
; #define PG8_MMA(ai, bj, At, Bt) do { __builtin_amdgcn_s_setprio(1); _Pragma("unroll") for (int m = 0; m < 4; ++m) _Pragma("unroll") for (int n = 0; n < 2; ++n) _Pragma("unroll") for (int k = 0; k < 2; ++k) \
;         acc[ai][bj][m][n] = __builtin_amdgcn_mfma_f32_16x16x32_bf16(Bt[n][k], At[m][k], acc[ai][bj][m][n], 0, 0, 0); __builtin_amdgcn_s_setprio(0); } while (0)
; #define PG8_WAIT_V(n) asm volatile("s_waitcnt vmcnt(" #n ")" ::: "memory")
; #define PG8_WAIT_L(n) asm volatile("s_waitcnt lgkmcnt(" #n ")" ::: "memory")
; #define PG8_BAR __builtin_amdgcn_s_barrier()
; #define PG8_SCHED __builtin_amdgcn_sched_barrier(0)
; template <class Epi, class Sched, bool ALIGN_EPI = false, bool SP2 = false>
; __device__ __forceinline__ void gemm_phase(PG8_LAS unsigned char* lds, const Gemm g, const Sched& S, const Epi& E) {
;     ...
;             PG8_LDB(B0, 1, 0); PG8_LDB(B1, 1, 1); PG8_SCHED; PG8_LDA(At, 1, 0); PG8_STAGE(PG8_SA(0, 1), a2 + hstep, voffA);
;             PG8_WAIT_V(8); PG8_WAIT_L(0); PG8_BAR; PG8_MMA(0, 0, At, B0); PG8_MMA(0, 1, At, B1); PG8_BAR; PG8_SCHED;
;             PG8_LDA(At, 1, 1); PG8_STAGE(PG8_SB(1, 0), b3, voffB); PG8_STAGE(PG8_SB(1, 1), b3 + hstep, voffB); PG8_STAGE(PG8_SA(1, 0), a3, voffA);
;             PG8_WAIT_V(8); PG8_WAIT_L(0); PG8_BAR; if (full) { PG8_MMA(1, 0, At, B0); PG8_MMA(1, 1, At, B1); } PG8_BAR; PG8_SCHED;
.LBB0_918:
	s_barrier
	s_add_i32 s4, 0, 0x18000
	v_add_u32_e32 v128, s4, v195
	s_add_i32 s5, 0, 0x1c000
	ds_read_b128 v[146:149], v128
	ds_read_b128 v[150:153], v128 offset:1024
	ds_read_b128 v[154:157], v128 offset:2048
	ds_read_b128 v[158:161], v128 offset:3072
	v_add_u32_e32 v128, s5, v195
	ds_read_b128 v[130:133], v128
	ds_read_b128 v[134:137], v128 offset:1024
	ds_read_b128 v[138:141], v128 offset:2048
	ds_read_b128 v[142:145], v128 offset:3072
	s_add_u32 s2, s34, 0x40000
	s_addc_u32 s3, s35, 0
	s_mov_b32 m0, s73
	v_lshl_add_u64 v[196:197], s[2:3], 0, v[206:207]
	s_waitcnt lgkmcnt(7)
	ds_read_b128 v[162:165], v242 offset:32768
	ds_read_b128 v[166:169], v242 offset:33792
	ds_read_b128 v[170:173], v242 offset:34816
	ds_read_b128 v[174:177], v242 offset:35840
	ds_read_b128 v[178:181], v242 offset:36864
	ds_read_b128 v[182:185], v242 offset:37888
	ds_read_b128 v[186:189], v242 offset:38912
	ds_read_b128 v[190:193], v242 offset:39936
	global_load_lds_dwordx4 v[196:197], off
	v_lshl_add_u64 v[196:197], s[2:3], 0, v[210:211]
	s_mov_b32 m0, s77
	s_nop 0
	global_load_lds_dwordx4 v[196:197], off
	s_waitcnt vmcnt(8)
	s_waitcnt lgkmcnt(0)
	s_barrier
	s_setprio 1
	v_mfma_f32_16x16x32_bf16 v[124:127], v[146:149], v[162:165], v[124:127]
	v_mfma_f32_16x16x32_bf16 v[120:123], v[154:157], v[162:165], v[120:123]
	v_mfma_f32_16x16x32_bf16 v[116:119], v[146:149], v[170:173], v[116:119]
	v_mfma_f32_16x16x32_bf16 v[112:115], v[154:157], v[170:173], v[112:115]
	v_mfma_f32_16x16x32_bf16 v[104:107], v[146:149], v[178:181], v[104:107]
	v_mfma_f32_16x16x32_bf16 v[96:99], v[154:157], v[178:181], v[96:99]
	v_mfma_f32_16x16x32_bf16 v[88:91], v[146:149], v[186:189], v[88:91]
	v_mfma_f32_16x16x32_bf16 v[80:83], v[154:157], v[186:189], v[80:83]
	v_mfma_f32_16x16x32_bf16 v[124:127], v[150:153], v[166:169], v[124:127]
	v_mfma_f32_16x16x32_bf16 v[120:123], v[158:161], v[166:169], v[120:123]
	v_mfma_f32_16x16x32_bf16 v[116:119], v[150:153], v[174:177], v[116:119]
	v_mfma_f32_16x16x32_bf16 v[112:115], v[158:161], v[174:177], v[112:115]
	v_mfma_f32_16x16x32_bf16 v[104:107], v[150:153], v[182:185], v[104:107]
	v_mfma_f32_16x16x32_bf16 v[96:99], v[158:161], v[182:185], v[96:99]
	v_mfma_f32_16x16x32_bf16 v[88:91], v[150:153], v[190:193], v[88:91]
	v_mfma_f32_16x16x32_bf16 v[80:83], v[158:161], v[190:193], v[80:83]
	v_mfma_f32_16x16x32_bf16 v[108:111], v[130:133], v[162:165], v[108:111]
	v_mfma_f32_16x16x32_bf16 v[100:103], v[138:141], v[162:165], v[100:103]
	v_mfma_f32_16x16x32_bf16 v[92:95], v[130:133], v[170:173], v[92:95]
	v_mfma_f32_16x16x32_bf16 v[84:87], v[138:141], v[170:173], v[84:87]
	v_mfma_f32_16x16x32_bf16 v[76:79], v[130:133], v[178:181], v[76:79]
	v_mfma_f32_16x16x32_bf16 v[72:75], v[138:141], v[178:181], v[72:75]
	v_mfma_f32_16x16x32_bf16 v[68:71], v[130:133], v[186:189], v[68:71]
	v_mfma_f32_16x16x32_bf16 v[56:59], v[138:141], v[186:189], v[56:59]
	v_mfma_f32_16x16x32_bf16 v[108:111], v[134:137], v[166:169], v[108:111]
	v_mfma_f32_16x16x32_bf16 v[100:103], v[142:145], v[166:169], v[100:103]
	v_mfma_f32_16x16x32_bf16 v[92:95], v[134:137], v[174:177], v[92:95]
	v_mfma_f32_16x16x32_bf16 v[84:87], v[142:145], v[174:177], v[84:87]
	v_mfma_f32_16x16x32_bf16 v[76:79], v[134:137], v[182:185], v[76:79]
	v_mfma_f32_16x16x32_bf16 v[72:75], v[142:145], v[182:185], v[72:75]
	v_mfma_f32_16x16x32_bf16 v[68:71], v[134:137], v[190:193], v[68:71]
	v_mfma_f32_16x16x32_bf16 v[56:59], v[142:145], v[190:193], v[56:59]
	s_setprio 0
	s_barrier
	s_add_i32 s2, s4, s65
	v_lshl_add_u64 v[196:197], v[222:223], 0, s[26:27]
	s_mov_b32 m0, s2
	ds_read_b128 v[186:189], v242 offset:49152
	ds_read_b128 v[190:193], v242 offset:50176
	ds_read_b128 v[178:181], v242 offset:51200
	ds_read_b128 v[182:185], v242 offset:52224
	ds_read_b128 v[170:173], v242 offset:53248
	ds_read_b128 v[174:177], v242 offset:54272
	ds_read_b128 v[162:165], v242 offset:55296
	ds_read_b128 v[166:169], v242 offset:56320
	global_load_lds_dwordx4 v[196:197], off
	s_add_i32 m0, s2, 0x2000
	s_add_u32 s2, s28, 0x40080
	v_lshl_add_u64 v[196:197], v[224:225], 0, s[26:27]
	s_addc_u32 s3, s29, 0
	s_add_i32 s4, s5, s65
	global_load_lds_dwordx4 v[196:197], off
	v_lshl_add_u64 v[196:197], s[2:3], 0, v[208:209]
	s_mov_b32 m0, s4
	s_and_b64 vcc, exec, s[38:39]
	global_load_lds_dwordx4 v[196:197], off
	v_lshl_add_u64 v[196:197], s[2:3], 0, v[212:213]
	s_add_i32 m0, s4, 0x2000
	s_nop 0
	global_load_lds_dwordx4 v[196:197], off
	v_lshl_add_u64 v[196:197], v[226:227], 0, s[26:27]
	s_mov_b32 m0, s81
	s_nop 0
	global_load_lds_dwordx4 v[196:197], off
	v_lshl_add_u64 v[196:197], v[228:229], 0, s[26:27]
	s_mov_b32 m0, s88
	s_nop 0
	global_load_lds_dwordx4 v[196:197], off
	s_waitcnt vmcnt(8)
	s_waitcnt lgkmcnt(0)
	s_barrier
	s_cbranch_vccnz .LBB0_915
	s_setprio 1
	v_mfma_f32_16x16x32_bf16 v[64:67], v[146:149], v[186:189], v[64:67]
	v_mfma_f32_16x16x32_bf16 v[60:63], v[154:157], v[186:189], v[60:63]
	v_mfma_f32_16x16x32_bf16 v[44:47], v[146:149], v[178:181], v[44:47]
	v_mfma_f32_16x16x32_bf16 v[40:43], v[154:157], v[178:181], v[40:43]
	v_mfma_f32_16x16x32_bf16 v[28:31], v[146:149], v[170:173], v[28:31]
	v_mfma_f32_16x16x32_bf16 v[24:27], v[154:157], v[170:173], v[24:27]
	v_mfma_f32_16x16x32_bf16 v[12:15], v[146:149], v[162:165], v[12:15]
	v_mfma_f32_16x16x32_bf16 v[8:11], v[154:157], v[162:165], v[8:11]
	v_mfma_f32_16x16x32_bf16 v[64:67], v[150:153], v[190:193], v[64:67]
	v_mfma_f32_16x16x32_bf16 v[60:63], v[158:161], v[190:193], v[60:63]
	v_mfma_f32_16x16x32_bf16 v[44:47], v[150:153], v[182:185], v[44:47]
	v_mfma_f32_16x16x32_bf16 v[40:43], v[158:161], v[182:185], v[40:43]
	v_mfma_f32_16x16x32_bf16 v[28:31], v[150:153], v[174:177], v[28:31]
	v_mfma_f32_16x16x32_bf16 v[24:27], v[158:161], v[174:177], v[24:27]
	v_mfma_f32_16x16x32_bf16 v[12:15], v[150:153], v[166:169], v[12:15]
	v_mfma_f32_16x16x32_bf16 v[8:11], v[158:161], v[166:169], v[8:11]
	v_mfma_f32_16x16x32_bf16 v[52:55], v[130:133], v[186:189], v[52:55]
	v_mfma_f32_16x16x32_bf16 v[48:51], v[138:141], v[186:189], v[48:51]
	v_mfma_f32_16x16x32_bf16 v[36:39], v[130:133], v[178:181], v[36:39]
	v_mfma_f32_16x16x32_bf16 v[32:35], v[138:141], v[178:181], v[32:35]
	v_mfma_f32_16x16x32_bf16 v[20:23], v[130:133], v[170:173], v[20:23]
	v_mfma_f32_16x16x32_bf16 v[16:19], v[138:141], v[170:173], v[16:19]
	v_mfma_f32_16x16x32_bf16 v[4:7], v[130:133], v[162:165], v[4:7]
	v_mfma_f32_16x16x32_bf16 v[0:3], v[138:141], v[162:165], v[0:3]
	v_mfma_f32_16x16x32_bf16 v[52:55], v[134:137], v[190:193], v[52:55]
	v_mfma_f32_16x16x32_bf16 v[48:51], v[142:145], v[190:193], v[48:51]
	v_mfma_f32_16x16x32_bf16 v[36:39], v[134:137], v[182:185], v[36:39]
	v_mfma_f32_16x16x32_bf16 v[32:35], v[142:145], v[182:185], v[32:35]
	v_mfma_f32_16x16x32_bf16 v[20:23], v[134:137], v[174:177], v[20:23]
	v_mfma_f32_16x16x32_bf16 v[16:19], v[142:145], v[174:177], v[16:19]
	v_mfma_f32_16x16x32_bf16 v[4:7], v[134:137], v[166:169], v[4:7]
	v_mfma_f32_16x16x32_bf16 v[0:3], v[142:145], v[166:169], v[0:3]
	s_setprio 0
	s_branch .LBB0_915

; #define PG8_STAGE(bufoff, gbase, voff) do { _Pragma("unroll") for (int _i = 0; _i < 2; ++_i) \
;         __builtin_amdgcn_global_load_lds((const unsigned*)((const char*)(gbase) + (voff)[_i]), (PG8_LAS unsigned*)(lds + (bufoff) + ldsw + _i * 8192), 16, 0, 0); } while (0)
; #define PG8_LDA(dst, b, h) do { _Pragma("unroll") for (int m = 0; m < 4; ++m) _Pragma("unroll") for (int k = 0; k < 2; ++k) dst[m][k] = *(const PG8_LAS bf16x8*)(lds + PG8_SA(b, h) + aoff + m * 2048 + k * 1024); } while (0)
; #define PG8_LDB(dst, b, h) do { _Pragma("unroll") for (int n = 0; n < 2; ++n) _Pragma("unroll") for (int k = 0; k < 2; ++k) dst[n][k] = *(const PG8_LAS bf16x8*)(lds + PG8_SB(b, h) + boff + n * 2048 + k * 1024); } while (0)
; #define PG8_MMA(ai, bj, At, Bt) do { __builtin_amdgcn_s_setprio(1); _Pragma("unroll") for (int m = 0; m < 4; ++m) _Pragma("unroll") for (int n = 0; n < 2; ++n) _Pragma("unroll") for (int k = 0; k < 2; ++k) \
;         acc[ai][bj][m][n] = __builtin_amdgcn_mfma_f32_16x16x32_bf16(Bt[n][k], At[m][k], acc[ai][bj][m][n], 0, 0, 0); __builtin_amdgcn_s_setprio(0); } while (0)
; #define PG8_WAIT_V(n) asm volatile("s_waitcnt vmcnt(" #n ")" ::: "memory")
; #define PG8_WAIT_L(n) asm volatile("s_waitcnt lgkmcnt(" #n ")" ::: "memory")
; template <class Epi, class Sched, bool ALIGN_EPI = false, bool SP2 = false>
; __device__ __forceinline__ void gemm_phase(PG8_LAS unsigned char* lds, const Gemm g, const Sched& S, const Epi& E) {
;     ...
;             const bool last = (t == ntu - 2);
;             const char* a1 = cA + (size_t)(t + 1) * kstep;
;             const char* a2 = last ? nA : cA + (size_t)(t + 2) * kstep; const char* b2 = last ? nB : cB + (size_t)(t + 2) * kstep;
;             const char* a3 = a2 + kstep; const char* b3 = b2 + kstep;
;             if (last && has_next) S.a_ready(nxt);
;             if constexpr (SP2) {
;             PG8_LDB(B0, 0, 0); PG8_LDB(B1, 0, 1); PG8_SCHED; PG8_LDA(At, 0, 0); PG8_STAGE(PG8_SA(1, 1), a1 + hstep, voffA);
;             PG8_WAIT_V(8); PG8_WAIT_L(0); PG8_BAR; PG8_MMA(0, 0, At, B0); PG8_MMA(0, 1, At, B1); PG8_BAR; PG8_SCHED;
;             PG8_LDA(At, 0, 1); PG8_STAGE(PG8_SB(0, 0), b2, voffB); PG8_STAGE(PG8_SB(0, 1), b2 + hstep, voffB); PG8_STAGE(PG8_SA(0, 0), a2, voffA);
;             PG8_WAIT_V(8); PG8_WAIT_L(0); PG8_BAR; if (full) { PG8_MMA(1, 0, At, B0); PG8_MMA(1, 1, At, B1); } PG8_BAR; PG8_SCHED;
.LBB0_1079:
	s_add_u32 s2, s48, 0xfffc0080
	s_addc_u32 s3, s49, -1
	s_add_i32 s4, 0, 0x10000
	s_cmp_eq_u32 s12, 12
	s_cselect_b32 s35, s1, s3
	s_cselect_b32 s34, s90, s2
	v_add_u32_e32 v128, s4, v226
	s_cselect_b32 s29, s75, s50
	s_cselect_b32 s28, s91, s92
	s_add_i32 s5, 0, 0x14000
	ds_read_b128 v[146:149], v128
	ds_read_b128 v[150:153], v128 offset:1024
	ds_read_b128 v[154:157], v128 offset:2048
	ds_read_b128 v[158:161], v128 offset:3072
	v_add_u32_e32 v128, s5, v226
	ds_read_b128 v[130:133], v128
	ds_read_b128 v[134:137], v128 offset:1024
	ds_read_b128 v[138:141], v128 offset:2048
	ds_read_b128 v[142:145], v128 offset:3072
	v_lshl_add_u64 v[196:197], s[48:49], 0, v[214:215]
	s_add_i32 m0, s70, 0xc000
	s_waitcnt lgkmcnt(7)
	ds_read_b128 v[162:165], v228
	ds_read_b128 v[166:169], v228 offset:1024
	ds_read_b128 v[170:173], v228 offset:2048
	ds_read_b128 v[174:177], v228 offset:3072
	ds_read_b128 v[178:181], v228 offset:4096
	ds_read_b128 v[182:185], v228 offset:5120
	ds_read_b128 v[186:189], v228 offset:6144
	ds_read_b128 v[190:193], v228 offset:7168
	global_load_lds_dwordx4 v[196:197], off
	v_lshl_add_u64 v[196:197], s[48:49], 0, v[216:217]
	s_add_i32 m0, s70, 0xe000
	s_nop 0
	global_load_lds_dwordx4 v[196:197], off
	s_waitcnt vmcnt(8)
	s_waitcnt lgkmcnt(0)
	s_barrier
	s_setprio 1
	v_mfma_f32_16x16x32_bf16 v[124:127], v[146:149], v[162:165], v[124:127]
	v_mfma_f32_16x16x32_bf16 v[120:123], v[154:157], v[162:165], v[120:123]
	v_mfma_f32_16x16x32_bf16 v[108:111], v[146:149], v[170:173], v[108:111]
	v_mfma_f32_16x16x32_bf16 v[104:107], v[154:157], v[170:173], v[104:107]
	v_mfma_f32_16x16x32_bf16 v[92:95], v[146:149], v[178:181], v[92:95]
	v_mfma_f32_16x16x32_bf16 v[88:91], v[154:157], v[178:181], v[88:91]
	v_mfma_f32_16x16x32_bf16 v[76:79], v[146:149], v[186:189], v[76:79]
	v_mfma_f32_16x16x32_bf16 v[72:75], v[154:157], v[186:189], v[72:75]
	v_mfma_f32_16x16x32_bf16 v[124:127], v[150:153], v[166:169], v[124:127]
	v_mfma_f32_16x16x32_bf16 v[120:123], v[158:161], v[166:169], v[120:123]
	v_mfma_f32_16x16x32_bf16 v[108:111], v[150:153], v[174:177], v[108:111]
	v_mfma_f32_16x16x32_bf16 v[104:107], v[158:161], v[174:177], v[104:107]
	v_mfma_f32_16x16x32_bf16 v[92:95], v[150:153], v[182:185], v[92:95]
	v_mfma_f32_16x16x32_bf16 v[88:91], v[158:161], v[182:185], v[88:91]
	v_mfma_f32_16x16x32_bf16 v[76:79], v[150:153], v[190:193], v[76:79]
	v_mfma_f32_16x16x32_bf16 v[72:75], v[158:161], v[190:193], v[72:75]
	v_mfma_f32_16x16x32_bf16 v[116:119], v[130:133], v[162:165], v[116:119]
	v_mfma_f32_16x16x32_bf16 v[112:115], v[138:141], v[162:165], v[112:115]
	v_mfma_f32_16x16x32_bf16 v[100:103], v[130:133], v[170:173], v[100:103]
	v_mfma_f32_16x16x32_bf16 v[96:99], v[138:141], v[170:173], v[96:99]
	v_mfma_f32_16x16x32_bf16 v[84:87], v[130:133], v[178:181], v[84:87]
	v_mfma_f32_16x16x32_bf16 v[80:83], v[138:141], v[178:181], v[80:83]
	v_mfma_f32_16x16x32_bf16 v[68:71], v[130:133], v[186:189], v[68:71]
	v_mfma_f32_16x16x32_bf16 v[64:67], v[138:141], v[186:189], v[64:67]
	v_mfma_f32_16x16x32_bf16 v[116:119], v[134:137], v[166:169], v[116:119]
	v_mfma_f32_16x16x32_bf16 v[112:115], v[142:145], v[166:169], v[112:115]
	v_mfma_f32_16x16x32_bf16 v[100:103], v[134:137], v[174:177], v[100:103]
	v_mfma_f32_16x16x32_bf16 v[96:99], v[142:145], v[174:177], v[96:99]
	v_mfma_f32_16x16x32_bf16 v[84:87], v[134:137], v[182:185], v[84:87]
	v_mfma_f32_16x16x32_bf16 v[80:83], v[142:145], v[182:185], v[80:83]
	v_mfma_f32_16x16x32_bf16 v[68:71], v[134:137], v[190:193], v[68:71]
	v_mfma_f32_16x16x32_bf16 v[64:67], v[142:145], v[190:193], v[64:67]
	s_setprio 0
	s_barrier
	s_add_i32 s2, s4, s65
	v_lshl_add_u64 v[218:219], s[28:29], 0, v[208:209]
	s_mov_b32 m0, s2
	ds_read_b128 v[186:189], v228 offset:16384
	ds_read_b128 v[190:193], v228 offset:17408
	ds_read_b128 v[178:181], v228 offset:18432
	ds_read_b128 v[182:185], v228 offset:19456
	ds_read_b128 v[170:173], v228 offset:20480
	ds_read_b128 v[174:177], v228 offset:21504
	ds_read_b128 v[162:165], v228 offset:22528
	ds_read_b128 v[166:169], v228 offset:23552
	global_load_lds_dwordx4 v[218:219], off
	s_add_i32 m0, s2, 0x2000
	s_add_u32 s2, s28, 0x40000
	v_lshl_add_u64 v[220:221], s[28:29], 0, v[212:213]
	s_addc_u32 s3, s29, 0
	s_add_i32 s4, s5, s65
	global_load_lds_dwordx4 v[220:221], off
	v_lshl_add_u64 v[196:197], s[2:3], 0, v[208:209]
	s_mov_b32 m0, s4
	v_lshl_add_u64 v[222:223], s[34:35], 0, v[206:207]
	global_load_lds_dwordx4 v[196:197], off
	v_lshl_add_u64 v[196:197], s[2:3], 0, v[212:213]
	s_add_i32 m0, s4, 0x2000
	v_lshl_add_u64 v[224:225], s[34:35], 0, v[210:211]
	global_load_lds_dwordx4 v[196:197], off
	s_mov_b32 m0, s70
	v_cndmask_b32_e64 v128, 0, 1, s[82:83]
	global_load_lds_dwordx4 v[222:223], off
	s_mov_b32 m0, s71
	v_cmp_ne_u32_e64 s[38:39], 1, v128
	global_load_lds_dwordx4 v[224:225], off
	s_waitcnt vmcnt(8)
	s_waitcnt lgkmcnt(0)
	s_andn2_b64 vcc, exec, s[82:83]
	s_barrier
	s_cbranch_vccnz .LBB0_1081
; #define PG8_MMA(ai, bj, At, Bt) do { __builtin_amdgcn_s_setprio(1); _Pragma("unroll") for (int m = 0; m < 4; ++m) _Pragma("unroll") for (int n = 0; n < 2; ++n) _Pragma("unroll") for (int k = 0; k < 2; ++k) \
;         acc[ai][bj][m][n] = __builtin_amdgcn_mfma_f32_16x16x32_bf16(Bt[n][k], At[m][k], acc[ai][bj][m][n], 0, 0, 0); __builtin_amdgcn_s_setprio(0); } while (0)
; #define PG8_WAIT_V(n) asm volatile("s_waitcnt vmcnt(" #n ")" ::: "memory")
; #define PG8_WAIT_L(n) asm volatile("s_waitcnt lgkmcnt(" #n ")" ::: "memory")
; #define PG8_BAR __builtin_amdgcn_s_barrier()
; #define PG8_SCHED __builtin_amdgcn_sched_barrier(0)
; template <class Epi, class Sched, bool ALIGN_EPI = false, bool SP2 = false>
; __device__ __forceinline__ void gemm_phase(PG8_LAS unsigned char* lds, const Gemm g, const Sched& S, const Epi& E) {
;     ...
;             PG8_WAIT_V(8); PG8_WAIT_L(0); PG8_BAR; if (full) { PG8_MMA(1, 0, At, B0); PG8_MMA(1, 1, At, B1); } PG8_BAR; PG8_SCHED;
	s_setprio 1
	v_mfma_f32_16x16x32_bf16 v[60:63], v[146:149], v[186:189], v[60:63]
	v_mfma_f32_16x16x32_bf16 v[52:55], v[154:157], v[186:189], v[52:55]
	v_mfma_f32_16x16x32_bf16 v[44:47], v[146:149], v[178:181], v[44:47]
	v_mfma_f32_16x16x32_bf16 v[36:39], v[154:157], v[178:181], v[36:39]
	v_mfma_f32_16x16x32_bf16 v[28:31], v[146:149], v[170:173], v[28:31]
	v_mfma_f32_16x16x32_bf16 v[20:23], v[154:157], v[170:173], v[20:23]
	v_mfma_f32_16x16x32_bf16 v[12:15], v[146:149], v[162:165], v[12:15]
	v_mfma_f32_16x16x32_bf16 v[4:7], v[154:157], v[162:165], v[4:7]
	v_mfma_f32_16x16x32_bf16 v[60:63], v[150:153], v[190:193], v[60:63]
	v_mfma_f32_16x16x32_bf16 v[52:55], v[158:161], v[190:193], v[52:55]
	v_mfma_f32_16x16x32_bf16 v[44:47], v[150:153], v[182:185], v[44:47]
	v_mfma_f32_16x16x32_bf16 v[36:39], v[158:161], v[182:185], v[36:39]
	v_mfma_f32_16x16x32_bf16 v[28:31], v[150:153], v[174:177], v[28:31]
	v_mfma_f32_16x16x32_bf16 v[20:23], v[158:161], v[174:177], v[20:23]
	v_mfma_f32_16x16x32_bf16 v[12:15], v[150:153], v[166:169], v[12:15]
	v_mfma_f32_16x16x32_bf16 v[4:7], v[158:161], v[166:169], v[4:7]
	v_mfma_f32_16x16x32_bf16 v[56:59], v[130:133], v[186:189], v[56:59]
	v_mfma_f32_16x16x32_bf16 v[48:51], v[138:141], v[186:189], v[48:51]
	v_mfma_f32_16x16x32_bf16 v[40:43], v[130:133], v[178:181], v[40:43]
	v_mfma_f32_16x16x32_bf16 v[32:35], v[138:141], v[178:181], v[32:35]
	v_mfma_f32_16x16x32_bf16 v[24:27], v[130:133], v[170:173], v[24:27]
	v_mfma_f32_16x16x32_bf16 v[16:19], v[138:141], v[170:173], v[16:19]
	v_mfma_f32_16x16x32_bf16 v[8:11], v[130:133], v[162:165], v[8:11]
	v_mfma_f32_16x16x32_bf16 v[0:3], v[138:141], v[162:165], v[0:3]
	v_mfma_f32_16x16x32_bf16 v[56:59], v[134:137], v[190:193], v[56:59]
	v_mfma_f32_16x16x32_bf16 v[48:51], v[142:145], v[190:193], v[48:51]
	v_mfma_f32_16x16x32_bf16 v[40:43], v[134:137], v[182:185], v[40:43]
	v_mfma_f32_16x16x32_bf16 v[32:35], v[142:145], v[182:185], v[32:35]
	v_mfma_f32_16x16x32_bf16 v[24:27], v[134:137], v[174:177], v[24:27]
	v_mfma_f32_16x16x32_bf16 v[16:19], v[142:145], v[174:177], v[16:19]
	v_mfma_f32_16x16x32_bf16 v[8:11], v[134:137], v[166:169], v[8:11]
	v_mfma_f32_16x16x32_bf16 v[0:3], v[142:145], v[166:169], v[0:3]
	s_setprio 0
; #define PG8_STAGE(bufoff, gbase, voff) do { _Pragma("unroll") for (int _i = 0; _i < 2; ++_i) \
;         __builtin_amdgcn_global_load_lds((const unsigned*)((const char*)(gbase) + (voff)[_i]), (PG8_LAS unsigned*)(lds + (bufoff) + ldsw + _i * 8192), 16, 0, 0); } while (0)
; #define PG8_LDA(dst, b, h) do { _Pragma("unroll") for (int m = 0; m < 4; ++m) _Pragma("unroll") for (int k = 0; k < 2; ++k) dst[m][k] = *(const PG8_LAS bf16x8*)(lds + PG8_SA(b, h) + aoff + m * 2048 + k * 1024); } while (0)
; #define PG8_LDB(dst, b, h) do { _Pragma("unroll") for (int n = 0; n < 2; ++n) _Pragma("unroll") for (int k = 0; k < 2; ++k) dst[n][k] = *(const PG8_LAS bf16x8*)(lds + PG8_SB(b, h) + boff + n * 2048 + k * 1024); } while (0)
; #define PG8_MMA(ai, bj, At, Bt) do { __builtin_amdgcn_s_setprio(1); _Pragma("unroll") for (int m = 0; m < 4; ++m) _Pragma("unroll") for (int n = 0; n < 2; ++n) _Pragma("unroll") for (int k = 0; k < 2; ++k) \
;         acc[ai][bj][m][n] = __builtin_amdgcn_mfma_f32_16x16x32_bf16(Bt[n][k], At[m][k], acc[ai][bj][m][n], 0, 0, 0); __builtin_amdgcn_s_setprio(0); } while (0)
; #define PG8_WAIT_V(n) asm volatile("s_waitcnt vmcnt(" #n ")" ::: "memory")
; #define PG8_WAIT_L(n) asm volatile("s_waitcnt lgkmcnt(" #n ")" ::: "memory")
; #define PG8_BAR __builtin_amdgcn_s_barrier()
; #define PG8_SCHED __builtin_amdgcn_sched_barrier(0)
; template <class Epi, class Sched, bool ALIGN_EPI = false, bool SP2 = false>
; __device__ __forceinline__ void gemm_phase(PG8_LAS unsigned char* lds, const Gemm g, const Sched& S, const Epi& E) {
;     ...
;             PG8_LDB(B0, 1, 0); PG8_LDB(B1, 1, 1); PG8_SCHED; PG8_LDA(At, 1, 0); PG8_STAGE(PG8_SA(0, 1), a2 + hstep, voffA);
;             PG8_WAIT_V(8); PG8_WAIT_L(0); PG8_BAR; PG8_MMA(0, 0, At, B0); PG8_MMA(0, 1, At, B1); PG8_BAR; PG8_SCHED;
;             PG8_LDA(At, 1, 1); PG8_STAGE(PG8_SB(1, 0), b3, voffB); PG8_STAGE(PG8_SB(1, 1), b3 + hstep, voffB); PG8_STAGE(PG8_SA(1, 0), a3, voffA);
;             PG8_WAIT_V(8); PG8_WAIT_L(0); PG8_BAR; if (full) { PG8_MMA(1, 0, At, B0); PG8_MMA(1, 1, At, B1); } PG8_BAR; PG8_SCHED;
.LBB0_1081:
	s_barrier
	s_add_i32 s4, 0, 0x18000
	v_add_u32_e32 v128, s4, v226
	s_add_i32 s5, 0, 0x1c000
	ds_read_b128 v[146:149], v128
	ds_read_b128 v[150:153], v128 offset:1024
	ds_read_b128 v[154:157], v128 offset:2048
	ds_read_b128 v[158:161], v128 offset:3072
	v_add_u32_e32 v128, s5, v226
	ds_read_b128 v[130:133], v128
	ds_read_b128 v[134:137], v128 offset:1024
	ds_read_b128 v[138:141], v128 offset:2048
	ds_read_b128 v[142:145], v128 offset:3072
	s_add_u32 s2, s34, 0x40000
	s_addc_u32 s3, s35, 0
	s_mov_b32 m0, s73
	v_lshl_add_u64 v[196:197], s[2:3], 0, v[206:207]
	s_waitcnt lgkmcnt(7)
	ds_read_b128 v[162:165], v228 offset:32768
	ds_read_b128 v[166:169], v228 offset:33792
	ds_read_b128 v[170:173], v228 offset:34816
	ds_read_b128 v[174:177], v228 offset:35840
	ds_read_b128 v[178:181], v228 offset:36864
	ds_read_b128 v[182:185], v228 offset:37888
	ds_read_b128 v[186:189], v228 offset:38912
	ds_read_b128 v[190:193], v228 offset:39936
	global_load_lds_dwordx4 v[196:197], off
	v_lshl_add_u64 v[196:197], s[2:3], 0, v[210:211]
	s_mov_b32 m0, s81
	s_nop 0
	global_load_lds_dwordx4 v[196:197], off
	s_waitcnt vmcnt(8)
	s_waitcnt lgkmcnt(0)
	s_barrier
	s_setprio 1
	v_mfma_f32_16x16x32_bf16 v[124:127], v[146:149], v[162:165], v[124:127]
	v_mfma_f32_16x16x32_bf16 v[120:123], v[154:157], v[162:165], v[120:123]
	v_mfma_f32_16x16x32_bf16 v[108:111], v[146:149], v[170:173], v[108:111]
	v_mfma_f32_16x16x32_bf16 v[104:107], v[154:157], v[170:173], v[104:107]
	v_mfma_f32_16x16x32_bf16 v[92:95], v[146:149], v[178:181], v[92:95]
	v_mfma_f32_16x16x32_bf16 v[88:91], v[154:157], v[178:181], v[88:91]
	v_mfma_f32_16x16x32_bf16 v[76:79], v[146:149], v[186:189], v[76:79]
	v_mfma_f32_16x16x32_bf16 v[72:75], v[154:157], v[186:189], v[72:75]
	v_mfma_f32_16x16x32_bf16 v[124:127], v[150:153], v[166:169], v[124:127]
	v_mfma_f32_16x16x32_bf16 v[120:123], v[158:161], v[166:169], v[120:123]
	v_mfma_f32_16x16x32_bf16 v[108:111], v[150:153], v[174:177], v[108:111]
	v_mfma_f32_16x16x32_bf16 v[104:107], v[158:161], v[174:177], v[104:107]
	v_mfma_f32_16x16x32_bf16 v[92:95], v[150:153], v[182:185], v[92:95]
	v_mfma_f32_16x16x32_bf16 v[88:91], v[158:161], v[182:185], v[88:91]
	v_mfma_f32_16x16x32_bf16 v[76:79], v[150:153], v[190:193], v[76:79]
	v_mfma_f32_16x16x32_bf16 v[72:75], v[158:161], v[190:193], v[72:75]
	v_mfma_f32_16x16x32_bf16 v[116:119], v[130:133], v[162:165], v[116:119]
	v_mfma_f32_16x16x32_bf16 v[112:115], v[138:141], v[162:165], v[112:115]
	v_mfma_f32_16x16x32_bf16 v[100:103], v[130:133], v[170:173], v[100:103]
	v_mfma_f32_16x16x32_bf16 v[96:99], v[138:141], v[170:173], v[96:99]
	v_mfma_f32_16x16x32_bf16 v[84:87], v[130:133], v[178:181], v[84:87]
	v_mfma_f32_16x16x32_bf16 v[80:83], v[138:141], v[178:181], v[80:83]
	v_mfma_f32_16x16x32_bf16 v[68:71], v[130:133], v[186:189], v[68:71]
	v_mfma_f32_16x16x32_bf16 v[64:67], v[138:141], v[186:189], v[64:67]
	v_mfma_f32_16x16x32_bf16 v[116:119], v[134:137], v[166:169], v[116:119]
	v_mfma_f32_16x16x32_bf16 v[112:115], v[142:145], v[166:169], v[112:115]
	v_mfma_f32_16x16x32_bf16 v[100:103], v[134:137], v[174:177], v[100:103]
	v_mfma_f32_16x16x32_bf16 v[96:99], v[142:145], v[174:177], v[96:99]
	v_mfma_f32_16x16x32_bf16 v[84:87], v[134:137], v[182:185], v[84:87]
	v_mfma_f32_16x16x32_bf16 v[80:83], v[142:145], v[182:185], v[80:83]
	v_mfma_f32_16x16x32_bf16 v[68:71], v[134:137], v[190:193], v[68:71]
	v_mfma_f32_16x16x32_bf16 v[64:67], v[142:145], v[190:193], v[64:67]
	s_setprio 0
	s_barrier
	s_add_i32 s2, s4, s65
	v_lshl_add_u64 v[196:197], v[218:219], 0, s[26:27]
	s_mov_b32 m0, s2
	ds_read_b128 v[186:189], v228 offset:49152
	ds_read_b128 v[190:193], v228 offset:50176
	ds_read_b128 v[178:181], v228 offset:51200
	ds_read_b128 v[182:185], v228 offset:52224
	ds_read_b128 v[170:173], v228 offset:53248
	ds_read_b128 v[174:177], v228 offset:54272
	ds_read_b128 v[162:165], v228 offset:55296
	ds_read_b128 v[166:169], v228 offset:56320
	global_load_lds_dwordx4 v[196:197], off
	s_add_i32 m0, s2, 0x2000
	s_add_u32 s2, s28, 0x40080
	v_lshl_add_u64 v[196:197], v[220:221], 0, s[26:27]
	s_addc_u32 s3, s29, 0
	s_add_i32 s4, s5, s65
	global_load_lds_dwordx4 v[196:197], off
	v_lshl_add_u64 v[196:197], s[2:3], 0, v[208:209]
	s_mov_b32 m0, s4
	s_and_b64 vcc, exec, s[38:39]
	global_load_lds_dwordx4 v[196:197], off
	v_lshl_add_u64 v[196:197], s[2:3], 0, v[212:213]
	s_add_i32 m0, s4, 0x2000
	s_nop 0
	global_load_lds_dwordx4 v[196:197], off
	v_lshl_add_u64 v[196:197], v[222:223], 0, s[26:27]
	s_mov_b32 m0, s84
	s_nop 0
	global_load_lds_dwordx4 v[196:197], off
	v_lshl_add_u64 v[196:197], v[224:225], 0, s[26:27]
	s_mov_b32 m0, s85
	s_nop 0
	global_load_lds_dwordx4 v[196:197], off
	s_waitcnt vmcnt(8)
	s_waitcnt lgkmcnt(0)
	s_barrier
	s_cbranch_vccnz .LBB0_1078
	s_setprio 1
	v_mfma_f32_16x16x32_bf16 v[60:63], v[146:149], v[186:189], v[60:63]
	v_mfma_f32_16x16x32_bf16 v[52:55], v[154:157], v[186:189], v[52:55]
	v_mfma_f32_16x16x32_bf16 v[44:47], v[146:149], v[178:181], v[44:47]
	v_mfma_f32_16x16x32_bf16 v[36:39], v[154:157], v[178:181], v[36:39]
	v_mfma_f32_16x16x32_bf16 v[28:31], v[146:149], v[170:173], v[28:31]
	v_mfma_f32_16x16x32_bf16 v[20:23], v[154:157], v[170:173], v[20:23]
	v_mfma_f32_16x16x32_bf16 v[12:15], v[146:149], v[162:165], v[12:15]
	v_mfma_f32_16x16x32_bf16 v[4:7], v[154:157], v[162:165], v[4:7]
	v_mfma_f32_16x16x32_bf16 v[60:63], v[150:153], v[190:193], v[60:63]
	v_mfma_f32_16x16x32_bf16 v[52:55], v[158:161], v[190:193], v[52:55]
	v_mfma_f32_16x16x32_bf16 v[44:47], v[150:153], v[182:185], v[44:47]
	v_mfma_f32_16x16x32_bf16 v[36:39], v[158:161], v[182:185], v[36:39]
	v_mfma_f32_16x16x32_bf16 v[28:31], v[150:153], v[174:177], v[28:31]
	v_mfma_f32_16x16x32_bf16 v[20:23], v[158:161], v[174:177], v[20:23]
	v_mfma_f32_16x16x32_bf16 v[12:15], v[150:153], v[166:169], v[12:15]
	v_mfma_f32_16x16x32_bf16 v[4:7], v[158:161], v[166:169], v[4:7]
	v_mfma_f32_16x16x32_bf16 v[56:59], v[130:133], v[186:189], v[56:59]
	v_mfma_f32_16x16x32_bf16 v[48:51], v[138:141], v[186:189], v[48:51]
	v_mfma_f32_16x16x32_bf16 v[40:43], v[130:133], v[178:181], v[40:43]
	v_mfma_f32_16x16x32_bf16 v[32:35], v[138:141], v[178:181], v[32:35]
	v_mfma_f32_16x16x32_bf16 v[24:27], v[130:133], v[170:173], v[24:27]
	v_mfma_f32_16x16x32_bf16 v[16:19], v[138:141], v[170:173], v[16:19]
	v_mfma_f32_16x16x32_bf16 v[8:11], v[130:133], v[162:165], v[8:11]
	v_mfma_f32_16x16x32_bf16 v[0:3], v[138:141], v[162:165], v[0:3]
	v_mfma_f32_16x16x32_bf16 v[56:59], v[134:137], v[190:193], v[56:59]
	v_mfma_f32_16x16x32_bf16 v[48:51], v[142:145], v[190:193], v[48:51]
	v_mfma_f32_16x16x32_bf16 v[40:43], v[134:137], v[182:185], v[40:43]
	v_mfma_f32_16x16x32_bf16 v[32:35], v[142:145], v[182:185], v[32:35]
	v_mfma_f32_16x16x32_bf16 v[24:27], v[134:137], v[174:177], v[24:27]
	v_mfma_f32_16x16x32_bf16 v[16:19], v[142:145], v[174:177], v[16:19]
	v_mfma_f32_16x16x32_bf16 v[8:11], v[134:137], v[166:169], v[8:11]
	v_mfma_f32_16x16x32_bf16 v[0:3], v[142:145], v[166:169], v[0:3]
	s_setprio 0
	s_branch .LBB0_1078

; #define PG8_STAGE(bufoff, gbase, voff) do { _Pragma("unroll") for (int _i = 0; _i < 2; ++_i) \
;         __builtin_amdgcn_global_load_lds((const unsigned*)((const char*)(gbase) + (voff)[_i]), (PG8_LAS unsigned*)(lds + (bufoff) + ldsw + _i * 8192), 16, 0, 0); } while (0)
; #define PG8_LDA(dst, b, h) do { _Pragma("unroll") for (int m = 0; m < 4; ++m) _Pragma("unroll") for (int k = 0; k < 2; ++k) dst[m][k] = *(const PG8_LAS bf16x8*)(lds + PG8_SA(b, h) + aoff + m * 2048 + k * 1024); } while (0)
; #define PG8_LDB(dst, b, h) do { _Pragma("unroll") for (int n = 0; n < 2; ++n) _Pragma("unroll") for (int k = 0; k < 2; ++k) dst[n][k] = *(const PG8_LAS bf16x8*)(lds + PG8_SB(b, h) + boff + n * 2048 + k * 1024); } while (0)
; #define PG8_MMA(ai, bj, At, Bt) do { __builtin_amdgcn_s_setprio(1); _Pragma("unroll") for (int m = 0; m < 4; ++m) _Pragma("unroll") for (int n = 0; n < 2; ++n) _Pragma("unroll") for (int k = 0; k < 2; ++k) \
;         acc[ai][bj][m][n] = __builtin_amdgcn_mfma_f32_16x16x32_bf16(Bt[n][k], At[m][k], acc[ai][bj][m][n], 0, 0, 0); __builtin_amdgcn_s_setprio(0); } while (0)
; #define PG8_WAIT_V(n) asm volatile("s_waitcnt vmcnt(" #n ")" ::: "memory")
; #define PG8_WAIT_L(n) asm volatile("s_waitcnt lgkmcnt(" #n ")" ::: "memory")
; template <class Epi, class Sched, bool ALIGN_EPI = false, bool SP2 = false>
; __device__ __forceinline__ void gemm_phase(PG8_LAS unsigned char* lds, const Gemm g, const Sched& S, const Epi& E) {
;     ...
;             const bool last = (t == ntu - 2);
;             const char* a1 = cA + (size_t)(t + 1) * kstep;
;             const char* a2 = last ? nA : cA + (size_t)(t + 2) * kstep; const char* b2 = last ? nB : cB + (size_t)(t + 2) * kstep;
;             const char* a3 = a2 + kstep; const char* b3 = b2 + kstep;
;             if (last && has_next) S.a_ready(nxt);
;             if constexpr (SP2) {
;             PG8_LDB(B0, 0, 0); PG8_LDB(B1, 0, 1); PG8_SCHED; PG8_LDA(At, 0, 0); PG8_STAGE(PG8_SA(1, 1), a1 + hstep, voffA);
;             PG8_WAIT_V(8); PG8_WAIT_L(0); PG8_BAR; PG8_MMA(0, 0, At, B0); PG8_MMA(0, 1, At, B1); PG8_BAR; PG8_SCHED;
;             PG8_LDA(At, 0, 1); PG8_STAGE(PG8_SB(0, 0), b2, voffB); PG8_STAGE(PG8_SB(0, 1), b2 + hstep, voffB); PG8_STAGE(PG8_SA(0, 0), a2, voffA);
;             PG8_WAIT_V(8); PG8_WAIT_L(0); PG8_BAR; if (full) { PG8_MMA(1, 0, At, B0); PG8_MMA(1, 1, At, B1); } PG8_BAR; PG8_SCHED;
.LBB0_1171:
	s_mov_b64 s[38:39], s[80:81]
	s_add_u32 s80, s38, 0x100
	s_addc_u32 s81, s39, 0
	s_add_i32 s2, 0, 0x10000
	s_cmp_eq_u32 s94, s95
	s_cselect_b32 s35, s77, s81
	s_cselect_b32 s34, s76, s80
	v_add_u32_e32 v128, s2, v195
	s_cselect_b32 s29, s79, s51
	s_cselect_b32 s28, s78, s50
	s_add_i32 s4, 0, 0x14000
	ds_read_b128 v[146:149], v128
	ds_read_b128 v[150:153], v128 offset:1024
	ds_read_b128 v[154:157], v128 offset:2048
	ds_read_b128 v[158:161], v128 offset:3072
	v_add_u32_e32 v128, s4, v195
	ds_read_b128 v[130:133], v128
	ds_read_b128 v[134:137], v128 offset:1024
	ds_read_b128 v[138:141], v128 offset:2048
	ds_read_b128 v[142:145], v128 offset:3072
	v_lshl_add_u64 v[196:197], s[38:39], 0, v[218:219]
	s_add_i32 m0, s70, 0xc000
	s_waitcnt lgkmcnt(7)
	ds_read_b128 v[162:165], v242
	ds_read_b128 v[166:169], v242 offset:1024
	ds_read_b128 v[170:173], v242 offset:2048
	ds_read_b128 v[174:177], v242 offset:3072
	ds_read_b128 v[178:181], v242 offset:4096
	ds_read_b128 v[182:185], v242 offset:5120
	ds_read_b128 v[186:189], v242 offset:6144
	ds_read_b128 v[190:193], v242 offset:7168
	global_load_lds_dwordx4 v[196:197], off
	v_lshl_add_u64 v[196:197], s[38:39], 0, v[220:221]
	s_add_i32 m0, s70, 0xe000
	s_nop 0
	global_load_lds_dwordx4 v[196:197], off
	s_waitcnt vmcnt(8)
	s_waitcnt lgkmcnt(0)
	s_barrier
	s_setprio 1
	v_mfma_f32_16x16x32_bf16 v[124:127], v[146:149], v[162:165], v[124:127]
	v_mfma_f32_16x16x32_bf16 v[120:123], v[154:157], v[162:165], v[120:123]
	v_mfma_f32_16x16x32_bf16 v[116:119], v[146:149], v[170:173], v[116:119]
	v_mfma_f32_16x16x32_bf16 v[112:115], v[154:157], v[170:173], v[112:115]
	v_mfma_f32_16x16x32_bf16 v[104:107], v[146:149], v[178:181], v[104:107]
	v_mfma_f32_16x16x32_bf16 v[96:99], v[154:157], v[178:181], v[96:99]
	v_mfma_f32_16x16x32_bf16 v[88:91], v[146:149], v[186:189], v[88:91]
	v_mfma_f32_16x16x32_bf16 v[80:83], v[154:157], v[186:189], v[80:83]
	v_mfma_f32_16x16x32_bf16 v[124:127], v[150:153], v[166:169], v[124:127]
	v_mfma_f32_16x16x32_bf16 v[120:123], v[158:161], v[166:169], v[120:123]
	v_mfma_f32_16x16x32_bf16 v[116:119], v[150:153], v[174:177], v[116:119]
	v_mfma_f32_16x16x32_bf16 v[112:115], v[158:161], v[174:177], v[112:115]
	v_mfma_f32_16x16x32_bf16 v[104:107], v[150:153], v[182:185], v[104:107]
	v_mfma_f32_16x16x32_bf16 v[96:99], v[158:161], v[182:185], v[96:99]
	v_mfma_f32_16x16x32_bf16 v[88:91], v[150:153], v[190:193], v[88:91]
	v_mfma_f32_16x16x32_bf16 v[80:83], v[158:161], v[190:193], v[80:83]
	v_mfma_f32_16x16x32_bf16 v[108:111], v[130:133], v[162:165], v[108:111]
	v_mfma_f32_16x16x32_bf16 v[100:103], v[138:141], v[162:165], v[100:103]
	v_mfma_f32_16x16x32_bf16 v[92:95], v[130:133], v[170:173], v[92:95]
	v_mfma_f32_16x16x32_bf16 v[84:87], v[138:141], v[170:173], v[84:87]
	v_mfma_f32_16x16x32_bf16 v[76:79], v[130:133], v[178:181], v[76:79]
	v_mfma_f32_16x16x32_bf16 v[72:75], v[138:141], v[178:181], v[72:75]
	v_mfma_f32_16x16x32_bf16 v[68:71], v[130:133], v[186:189], v[68:71]
	v_mfma_f32_16x16x32_bf16 v[56:59], v[138:141], v[186:189], v[56:59]
	v_mfma_f32_16x16x32_bf16 v[108:111], v[134:137], v[166:169], v[108:111]
	v_mfma_f32_16x16x32_bf16 v[100:103], v[142:145], v[166:169], v[100:103]
	v_mfma_f32_16x16x32_bf16 v[92:95], v[134:137], v[174:177], v[92:95]
	v_mfma_f32_16x16x32_bf16 v[84:87], v[142:145], v[174:177], v[84:87]
	v_mfma_f32_16x16x32_bf16 v[76:79], v[134:137], v[182:185], v[76:79]
	v_mfma_f32_16x16x32_bf16 v[72:75], v[142:145], v[182:185], v[72:75]
	v_mfma_f32_16x16x32_bf16 v[68:71], v[134:137], v[190:193], v[68:71]
	v_mfma_f32_16x16x32_bf16 v[56:59], v[142:145], v[190:193], v[56:59]
	s_setprio 0
	s_barrier
	s_add_i32 s2, s2, s65
	v_lshl_add_u64 v[222:223], s[28:29], 0, v[208:209]
	s_mov_b32 m0, s2
	ds_read_b128 v[186:189], v242 offset:16384
	ds_read_b128 v[190:193], v242 offset:17408
	ds_read_b128 v[178:181], v242 offset:18432
	ds_read_b128 v[182:185], v242 offset:19456
	ds_read_b128 v[170:173], v242 offset:20480
	ds_read_b128 v[174:177], v242 offset:21504
	ds_read_b128 v[162:165], v242 offset:22528
	ds_read_b128 v[166:169], v242 offset:23552
	global_load_lds_dwordx4 v[222:223], off
	s_add_i32 m0, s2, 0x2000
	s_add_u32 s2, s28, 0xb0000
	v_lshl_add_u64 v[224:225], s[28:29], 0, v[212:213]
	s_addc_u32 s3, s29, 0
	s_add_i32 s4, s4, s65
	global_load_lds_dwordx4 v[224:225], off
	v_lshl_add_u64 v[196:197], s[2:3], 0, v[208:209]
	s_mov_b32 m0, s4
	v_lshl_add_u64 v[226:227], s[34:35], 0, v[206:207]
	global_load_lds_dwordx4 v[196:197], off
	v_lshl_add_u64 v[196:197], s[2:3], 0, v[212:213]
	s_add_i32 m0, s4, 0x2000
	v_lshl_add_u64 v[228:229], s[34:35], 0, v[210:211]
	global_load_lds_dwordx4 v[196:197], off
	s_mov_b32 m0, s70
	v_cndmask_b32_e64 v128, 0, 1, s[48:49]
	global_load_lds_dwordx4 v[226:227], off
	s_mov_b32 m0, s71
	v_cmp_ne_u32_e64 s[38:39], 1, v128
	global_load_lds_dwordx4 v[228:229], off
	s_waitcnt vmcnt(8)
	s_waitcnt lgkmcnt(0)
	s_andn2_b64 vcc, exec, s[48:49]
	s_barrier
	s_cbranch_vccnz .LBB0_1173
; #define PG8_MMA(ai, bj, At, Bt) do { __builtin_amdgcn_s_setprio(1); _Pragma("unroll") for (int m = 0; m < 4; ++m) _Pragma("unroll") for (int n = 0; n < 2; ++n) _Pragma("unroll") for (int k = 0; k < 2; ++k) \
;         acc[ai][bj][m][n] = __builtin_amdgcn_mfma_f32_16x16x32_bf16(Bt[n][k], At[m][k], acc[ai][bj][m][n], 0, 0, 0); __builtin_amdgcn_s_setprio(0); } while (0)
; #define PG8_WAIT_V(n) asm volatile("s_waitcnt vmcnt(" #n ")" ::: "memory")
; #define PG8_WAIT_L(n) asm volatile("s_waitcnt lgkmcnt(" #n ")" ::: "memory")
; #define PG8_BAR __builtin_amdgcn_s_barrier()
; #define PG8_SCHED __builtin_amdgcn_sched_barrier(0)
; template <class Epi, class Sched, bool ALIGN_EPI = false, bool SP2 = false>
; __device__ __forceinline__ void gemm_phase(PG8_LAS unsigned char* lds, const Gemm g, const Sched& S, const Epi& E) {
;     ...
;             PG8_WAIT_V(8); PG8_WAIT_L(0); PG8_BAR; if (full) { PG8_MMA(1, 0, At, B0); PG8_MMA(1, 1, At, B1); } PG8_BAR; PG8_SCHED;
	s_setprio 1
	v_mfma_f32_16x16x32_bf16 v[64:67], v[146:149], v[186:189], v[64:67]
	v_mfma_f32_16x16x32_bf16 v[60:63], v[154:157], v[186:189], v[60:63]
	v_mfma_f32_16x16x32_bf16 v[44:47], v[146:149], v[178:181], v[44:47]
	v_mfma_f32_16x16x32_bf16 v[40:43], v[154:157], v[178:181], v[40:43]
	v_mfma_f32_16x16x32_bf16 v[28:31], v[146:149], v[170:173], v[28:31]
	v_mfma_f32_16x16x32_bf16 v[24:27], v[154:157], v[170:173], v[24:27]
	v_mfma_f32_16x16x32_bf16 v[12:15], v[146:149], v[162:165], v[12:15]
	v_mfma_f32_16x16x32_bf16 v[8:11], v[154:157], v[162:165], v[8:11]
	v_mfma_f32_16x16x32_bf16 v[64:67], v[150:153], v[190:193], v[64:67]
	v_mfma_f32_16x16x32_bf16 v[60:63], v[158:161], v[190:193], v[60:63]
	v_mfma_f32_16x16x32_bf16 v[44:47], v[150:153], v[182:185], v[44:47]
	v_mfma_f32_16x16x32_bf16 v[40:43], v[158:161], v[182:185], v[40:43]
	v_mfma_f32_16x16x32_bf16 v[28:31], v[150:153], v[174:177], v[28:31]
	v_mfma_f32_16x16x32_bf16 v[24:27], v[158:161], v[174:177], v[24:27]
	v_mfma_f32_16x16x32_bf16 v[12:15], v[150:153], v[166:169], v[12:15]
	v_mfma_f32_16x16x32_bf16 v[8:11], v[158:161], v[166:169], v[8:11]
	v_mfma_f32_16x16x32_bf16 v[52:55], v[130:133], v[186:189], v[52:55]
	v_mfma_f32_16x16x32_bf16 v[48:51], v[138:141], v[186:189], v[48:51]
	v_mfma_f32_16x16x32_bf16 v[36:39], v[130:133], v[178:181], v[36:39]
	v_mfma_f32_16x16x32_bf16 v[32:35], v[138:141], v[178:181], v[32:35]
	v_mfma_f32_16x16x32_bf16 v[20:23], v[130:133], v[170:173], v[20:23]
	v_mfma_f32_16x16x32_bf16 v[16:19], v[138:141], v[170:173], v[16:19]
	v_mfma_f32_16x16x32_bf16 v[4:7], v[130:133], v[162:165], v[4:7]
	v_mfma_f32_16x16x32_bf16 v[0:3], v[138:141], v[162:165], v[0:3]
	v_mfma_f32_16x16x32_bf16 v[52:55], v[134:137], v[190:193], v[52:55]
	v_mfma_f32_16x16x32_bf16 v[48:51], v[142:145], v[190:193], v[48:51]
	v_mfma_f32_16x16x32_bf16 v[36:39], v[134:137], v[182:185], v[36:39]
	v_mfma_f32_16x16x32_bf16 v[32:35], v[142:145], v[182:185], v[32:35]
	v_mfma_f32_16x16x32_bf16 v[20:23], v[134:137], v[174:177], v[20:23]
	v_mfma_f32_16x16x32_bf16 v[16:19], v[142:145], v[174:177], v[16:19]
	v_mfma_f32_16x16x32_bf16 v[4:7], v[134:137], v[166:169], v[4:7]
	v_mfma_f32_16x16x32_bf16 v[0:3], v[142:145], v[166:169], v[0:3]
	s_setprio 0
; #define PG8_STAGE(bufoff, gbase, voff) do { _Pragma("unroll") for (int _i = 0; _i < 2; ++_i) \
;         __builtin_amdgcn_global_load_lds((const unsigned*)((const char*)(gbase) + (voff)[_i]), (PG8_LAS unsigned*)(lds + (bufoff) + ldsw + _i * 8192), 16, 0, 0); } while (0)
; #define PG8_LDA(dst, b, h) do { _Pragma("unroll") for (int m = 0; m < 4; ++m) _Pragma("unroll") for (int k = 0; k < 2; ++k) dst[m][k] = *(const PG8_LAS bf16x8*)(lds + PG8_SA(b, h) + aoff + m * 2048 + k * 1024); } while (0)
; #define PG8_LDB(dst, b, h) do { _Pragma("unroll") for (int n = 0; n < 2; ++n) _Pragma("unroll") for (int k = 0; k < 2; ++k) dst[n][k] = *(const PG8_LAS bf16x8*)(lds + PG8_SB(b, h) + boff + n * 2048 + k * 1024); } while (0)
; #define PG8_MMA(ai, bj, At, Bt) do { __builtin_amdgcn_s_setprio(1); _Pragma("unroll") for (int m = 0; m < 4; ++m) _Pragma("unroll") for (int n = 0; n < 2; ++n) _Pragma("unroll") for (int k = 0; k < 2; ++k) \
;         acc[ai][bj][m][n] = __builtin_amdgcn_mfma_f32_16x16x32_bf16(Bt[n][k], At[m][k], acc[ai][bj][m][n], 0, 0, 0); __builtin_amdgcn_s_setprio(0); } while (0)
; #define PG8_WAIT_V(n) asm volatile("s_waitcnt vmcnt(" #n ")" ::: "memory")
; #define PG8_WAIT_L(n) asm volatile("s_waitcnt lgkmcnt(" #n ")" ::: "memory")
; #define PG8_BAR __builtin_amdgcn_s_barrier()
; #define PG8_SCHED __builtin_amdgcn_sched_barrier(0)
; template <class Epi, class Sched, bool ALIGN_EPI = false, bool SP2 = false>
; __device__ __forceinline__ void gemm_phase(PG8_LAS unsigned char* lds, const Gemm g, const Sched& S, const Epi& E) {
;     ...
;             PG8_LDB(B0, 1, 0); PG8_LDB(B1, 1, 1); PG8_SCHED; PG8_LDA(At, 1, 0); PG8_STAGE(PG8_SA(0, 1), a2 + hstep, voffA);
;             PG8_WAIT_V(8); PG8_WAIT_L(0); PG8_BAR; PG8_MMA(0, 0, At, B0); PG8_MMA(0, 1, At, B1); PG8_BAR; PG8_SCHED;
;             PG8_LDA(At, 1, 1); PG8_STAGE(PG8_SB(1, 0), b3, voffB); PG8_STAGE(PG8_SB(1, 1), b3 + hstep, voffB); PG8_STAGE(PG8_SA(1, 0), a3, voffA);
;             PG8_WAIT_V(8); PG8_WAIT_L(0); PG8_BAR; if (full) { PG8_MMA(1, 0, At, B0); PG8_MMA(1, 1, At, B1); } PG8_BAR; PG8_SCHED;
.LBB0_1173:
	s_barrier
	s_add_i32 s4, 0, 0x18000
	v_add_u32_e32 v128, s4, v195
	s_add_i32 s5, 0, 0x1c000
	ds_read_b128 v[146:149], v128
	ds_read_b128 v[150:153], v128 offset:1024
	ds_read_b128 v[154:157], v128 offset:2048
	ds_read_b128 v[158:161], v128 offset:3072
	v_add_u32_e32 v128, s5, v195
	ds_read_b128 v[130:133], v128
	ds_read_b128 v[134:137], v128 offset:1024
	ds_read_b128 v[138:141], v128 offset:2048
	ds_read_b128 v[142:145], v128 offset:3072
	s_add_u32 s2, s34, 0xb0000
	s_addc_u32 s3, s35, 0
	s_mov_b32 m0, s73
	v_lshl_add_u64 v[196:197], s[2:3], 0, v[206:207]
	s_waitcnt lgkmcnt(7)
	ds_read_b128 v[162:165], v242 offset:32768
	ds_read_b128 v[166:169], v242 offset:33792
	ds_read_b128 v[170:173], v242 offset:34816
	ds_read_b128 v[174:177], v242 offset:35840
	ds_read_b128 v[178:181], v242 offset:36864
	ds_read_b128 v[182:185], v242 offset:37888
	ds_read_b128 v[186:189], v242 offset:38912
	ds_read_b128 v[190:193], v242 offset:39936
	global_load_lds_dwordx4 v[196:197], off
	v_lshl_add_u64 v[196:197], s[2:3], 0, v[210:211]
	s_mov_b32 m0, s82
	s_nop 0
	global_load_lds_dwordx4 v[196:197], off
	s_waitcnt vmcnt(8)
	s_waitcnt lgkmcnt(0)
	s_barrier
	s_setprio 1
	v_mfma_f32_16x16x32_bf16 v[124:127], v[146:149], v[162:165], v[124:127]
	v_mfma_f32_16x16x32_bf16 v[120:123], v[154:157], v[162:165], v[120:123]
	v_mfma_f32_16x16x32_bf16 v[116:119], v[146:149], v[170:173], v[116:119]
	v_mfma_f32_16x16x32_bf16 v[112:115], v[154:157], v[170:173], v[112:115]
	v_mfma_f32_16x16x32_bf16 v[104:107], v[146:149], v[178:181], v[104:107]
	v_mfma_f32_16x16x32_bf16 v[96:99], v[154:157], v[178:181], v[96:99]
	v_mfma_f32_16x16x32_bf16 v[88:91], v[146:149], v[186:189], v[88:91]
	v_mfma_f32_16x16x32_bf16 v[80:83], v[154:157], v[186:189], v[80:83]
	v_mfma_f32_16x16x32_bf16 v[124:127], v[150:153], v[166:169], v[124:127]
	v_mfma_f32_16x16x32_bf16 v[120:123], v[158:161], v[166:169], v[120:123]
	v_mfma_f32_16x16x32_bf16 v[116:119], v[150:153], v[174:177], v[116:119]
	v_mfma_f32_16x16x32_bf16 v[112:115], v[158:161], v[174:177], v[112:115]
	v_mfma_f32_16x16x32_bf16 v[104:107], v[150:153], v[182:185], v[104:107]
	v_mfma_f32_16x16x32_bf16 v[96:99], v[158:161], v[182:185], v[96:99]
	v_mfma_f32_16x16x32_bf16 v[88:91], v[150:153], v[190:193], v[88:91]
	v_mfma_f32_16x16x32_bf16 v[80:83], v[158:161], v[190:193], v[80:83]
	v_mfma_f32_16x16x32_bf16 v[108:111], v[130:133], v[162:165], v[108:111]
	v_mfma_f32_16x16x32_bf16 v[100:103], v[138:141], v[162:165], v[100:103]
	v_mfma_f32_16x16x32_bf16 v[92:95], v[130:133], v[170:173], v[92:95]
	v_mfma_f32_16x16x32_bf16 v[84:87], v[138:141], v[170:173], v[84:87]
	v_mfma_f32_16x16x32_bf16 v[76:79], v[130:133], v[178:181], v[76:79]
	v_mfma_f32_16x16x32_bf16 v[72:75], v[138:141], v[178:181], v[72:75]
	v_mfma_f32_16x16x32_bf16 v[68:71], v[130:133], v[186:189], v[68:71]
	v_mfma_f32_16x16x32_bf16 v[56:59], v[138:141], v[186:189], v[56:59]
	v_mfma_f32_16x16x32_bf16 v[108:111], v[134:137], v[166:169], v[108:111]
	v_mfma_f32_16x16x32_bf16 v[100:103], v[142:145], v[166:169], v[100:103]
	v_mfma_f32_16x16x32_bf16 v[92:95], v[134:137], v[174:177], v[92:95]
	v_mfma_f32_16x16x32_bf16 v[84:87], v[142:145], v[174:177], v[84:87]
	v_mfma_f32_16x16x32_bf16 v[76:79], v[134:137], v[182:185], v[76:79]
	v_mfma_f32_16x16x32_bf16 v[72:75], v[142:145], v[182:185], v[72:75]
	v_mfma_f32_16x16x32_bf16 v[68:71], v[134:137], v[190:193], v[68:71]
	v_mfma_f32_16x16x32_bf16 v[56:59], v[142:145], v[190:193], v[56:59]
	s_setprio 0
	s_barrier
	s_add_i32 s2, s4, s65
	v_lshl_add_u64 v[196:197], v[222:223], 0, s[26:27]
	s_mov_b32 m0, s2
	ds_read_b128 v[186:189], v242 offset:49152
	ds_read_b128 v[190:193], v242 offset:50176
	ds_read_b128 v[178:181], v242 offset:51200
	ds_read_b128 v[182:185], v242 offset:52224
	ds_read_b128 v[170:173], v242 offset:53248
	ds_read_b128 v[174:177], v242 offset:54272
	ds_read_b128 v[162:165], v242 offset:55296
	ds_read_b128 v[166:169], v242 offset:56320
	global_load_lds_dwordx4 v[196:197], off
	s_add_i32 m0, s2, 0x2000
	s_add_u32 s2, s28, 0xb0080
	v_lshl_add_u64 v[196:197], v[224:225], 0, s[26:27]
	s_addc_u32 s3, s29, 0
	s_add_i32 s4, s5, s65
	global_load_lds_dwordx4 v[196:197], off
	v_lshl_add_u64 v[196:197], s[2:3], 0, v[208:209]
	s_mov_b32 m0, s4
	s_and_b64 vcc, exec, s[38:39]
	global_load_lds_dwordx4 v[196:197], off
	v_lshl_add_u64 v[196:197], s[2:3], 0, v[212:213]
	s_add_i32 m0, s4, 0x2000
	s_nop 0
	global_load_lds_dwordx4 v[196:197], off
	v_lshl_add_u64 v[196:197], v[226:227], 0, s[26:27]
	s_mov_b32 m0, s83
	s_nop 0
	global_load_lds_dwordx4 v[196:197], off
	v_lshl_add_u64 v[196:197], v[228:229], 0, s[26:27]
	s_mov_b32 m0, s84
	s_nop 0
	global_load_lds_dwordx4 v[196:197], off
	s_waitcnt vmcnt(8)
	s_waitcnt lgkmcnt(0)
	s_barrier
	s_cbranch_vccnz .LBB0_1170
	s_setprio 1
	v_mfma_f32_16x16x32_bf16 v[64:67], v[146:149], v[186:189], v[64:67]
	v_mfma_f32_16x16x32_bf16 v[60:63], v[154:157], v[186:189], v[60:63]
	v_mfma_f32_16x16x32_bf16 v[44:47], v[146:149], v[178:181], v[44:47]
	v_mfma_f32_16x16x32_bf16 v[40:43], v[154:157], v[178:181], v[40:43]
	v_mfma_f32_16x16x32_bf16 v[28:31], v[146:149], v[170:173], v[28:31]
	v_mfma_f32_16x16x32_bf16 v[24:27], v[154:157], v[170:173], v[24:27]
	v_mfma_f32_16x16x32_bf16 v[12:15], v[146:149], v[162:165], v[12:15]
	v_mfma_f32_16x16x32_bf16 v[8:11], v[154:157], v[162:165], v[8:11]
	v_mfma_f32_16x16x32_bf16 v[64:67], v[150:153], v[190:193], v[64:67]
	v_mfma_f32_16x16x32_bf16 v[60:63], v[158:161], v[190:193], v[60:63]
	v_mfma_f32_16x16x32_bf16 v[44:47], v[150:153], v[182:185], v[44:47]
	v_mfma_f32_16x16x32_bf16 v[40:43], v[158:161], v[182:185], v[40:43]
	v_mfma_f32_16x16x32_bf16 v[28:31], v[150:153], v[174:177], v[28:31]
	v_mfma_f32_16x16x32_bf16 v[24:27], v[158:161], v[174:177], v[24:27]
	v_mfma_f32_16x16x32_bf16 v[12:15], v[150:153], v[166:169], v[12:15]
	v_mfma_f32_16x16x32_bf16 v[8:11], v[158:161], v[166:169], v[8:11]
	v_mfma_f32_16x16x32_bf16 v[52:55], v[130:133], v[186:189], v[52:55]
	v_mfma_f32_16x16x32_bf16 v[48:51], v[138:141], v[186:189], v[48:51]
	v_mfma_f32_16x16x32_bf16 v[36:39], v[130:133], v[178:181], v[36:39]
	v_mfma_f32_16x16x32_bf16 v[32:35], v[138:141], v[178:181], v[32:35]
	v_mfma_f32_16x16x32_bf16 v[20:23], v[130:133], v[170:173], v[20:23]
	v_mfma_f32_16x16x32_bf16 v[16:19], v[138:141], v[170:173], v[16:19]
	v_mfma_f32_16x16x32_bf16 v[4:7], v[130:133], v[162:165], v[4:7]
	v_mfma_f32_16x16x32_bf16 v[0:3], v[138:141], v[162:165], v[0:3]
	v_mfma_f32_16x16x32_bf16 v[52:55], v[134:137], v[190:193], v[52:55]
	v_mfma_f32_16x16x32_bf16 v[48:51], v[142:145], v[190:193], v[48:51]
	v_mfma_f32_16x16x32_bf16 v[36:39], v[134:137], v[182:185], v[36:39]
	v_mfma_f32_16x16x32_bf16 v[32:35], v[142:145], v[182:185], v[32:35]
	v_mfma_f32_16x16x32_bf16 v[20:23], v[134:137], v[174:177], v[20:23]
	v_mfma_f32_16x16x32_bf16 v[16:19], v[142:145], v[174:177], v[16:19]
	v_mfma_f32_16x16x32_bf16 v[4:7], v[134:137], v[166:169], v[4:7]
	v_mfma_f32_16x16x32_bf16 v[0:3], v[142:145], v[166:169], v[0:3]
	s_setprio 0
	s_branch .LBB0_1170
